# hand-written product-key top-k phase: token-per-lane scores (32x32x16 MFMA, keys as rows), f32 max/min sorting networks in-lane instead of 16-lane DPP tournament
# speedup vs baseline: 1.1081x; 1.0423x over previous
.LBB0_485:
	s_cmp_lt_i32 s56, 7
	s_cselect_b64 s[0:1], -1, 0
	s_and_b64 s[44:45], s[0:1], s[4:5]
	s_andn2_b64 vcc, exec, s[44:45]
	s_cbranch_vccnz .LBB0_540
	v_mbcnt_lo_u32_b32 v246, -1, 0
	v_mbcnt_hi_u32_b32 v246, -1, v246
	v_readlane_b32 s21, v248, 0
	s_andn2_b32 s26, s21, 63
	v_add_u32_e32 v242, s26, v246
	s_lshr_b32 s21, s21, 6
	s_mov_b32 s4, 0
	s_mov_b32 s5, -1
	s_mov_b32 s6, 0xffffff80
	s_mov_b32 s7, 0xffffffc0
	s_add_u32 s8, s54, 0x1c000000
	s_addc_u32 s9, s55, 0
	s_add_u32 s10, s54, 0x28000000
	s_addc_u32 s11, s55, 0
	s_add_u32 s12, s54, 0x28800000
	s_addc_u32 s13, s55, 0
	s_add_u32 s14, s54, 0x300000
	s_addc_u32 s15, s55, 0
	v_lshrrev_b32_e32 v245, 5, v246
	v_and_b32_e32 v247, 31, v246
	v_lshlrev_b32_e32 v239, 12, v247
	v_lshl_or_b32 v239, v245, 4, v239
	v_lshlrev_b32_e32 v241, 9, v247
	v_lshl_or_b32 v241, v245, 5, v241
	v_lshlrev_b32_e32 v240, 4, v247
	s_lshl_b32 s26, s21, 11
	s_add_i32 s26, s26, 0x10000
	v_add_u32_e32 v240, s26, v240
	v_and_b32_e32 v231, 15, v246
	v_xor_b32_e32 v231, v231, v245
	v_lshlrev_b32_e32 v231, 4, v231
	v_lshl_or_b32 v231, v247, 8, v231
	v_xor_b32_e32 v232, 32, v231
	v_xor_b32_e32 v233, 64, v231
	v_xor_b32_e32 v234, 0x60, v231
	v_xor_b32_e32 v235, 0x80, v231
	v_xor_b32_e32 v236, 0xa0, v231
	v_xor_b32_e32 v237, 0xc0, v231
	v_xor_b32_e32 v238, 0xe0, v231
	v_lshlrev_b32_e32 v247, 2, v245
	v_xor_b32_e32 v160, 0x7f, v247
	v_xor_b32_e32 v161, 0x7e, v247
	v_xor_b32_e32 v162, 0x7d, v247
	v_xor_b32_e32 v163, 0x7c, v247
	v_xor_b32_e32 v164, 0x77, v247
	v_xor_b32_e32 v165, 0x76, v247
	v_xor_b32_e32 v166, 0x75, v247
	v_xor_b32_e32 v167, 0x74, v247
	v_xor_b32_e32 v168, 0x6f, v247
	v_xor_b32_e32 v169, 0x6e, v247
	v_xor_b32_e32 v170, 0x6d, v247
	v_xor_b32_e32 v171, 0x6c, v247
	v_xor_b32_e32 v172, 0x67, v247
	v_xor_b32_e32 v173, 0x66, v247
	v_xor_b32_e32 v174, 0x65, v247
	v_xor_b32_e32 v175, 0x64, v247
	v_xor_b32_e32 v176, 0x5f, v247
	v_xor_b32_e32 v177, 0x5e, v247
	v_xor_b32_e32 v178, 0x5d, v247
	v_xor_b32_e32 v179, 0x5c, v247
	v_xor_b32_e32 v180, 0x57, v247
	v_xor_b32_e32 v181, 0x56, v247
	v_xor_b32_e32 v182, 0x55, v247
	v_xor_b32_e32 v183, 0x54, v247
	v_xor_b32_e32 v184, 0x4f, v247
	v_xor_b32_e32 v185, 0x4e, v247
	v_xor_b32_e32 v186, 0x4d, v247
	v_xor_b32_e32 v187, 0x4c, v247
	v_xor_b32_e32 v188, 0x47, v247
	v_xor_b32_e32 v189, 0x46, v247
	v_xor_b32_e32 v190, 0x45, v247
	v_xor_b32_e32 v191, 0x44, v247
	v_xor_b32_e32 v192, 63, v247
	v_xor_b32_e32 v193, 62, v247
	v_xor_b32_e32 v194, 61, v247
	v_xor_b32_e32 v195, 60, v247
	v_xor_b32_e32 v196, 55, v247
	v_xor_b32_e32 v204, 54, v247
	v_xor_b32_e32 v205, 53, v247
	v_xor_b32_e32 v206, 52, v247
	v_xor_b32_e32 v207, 47, v247
	v_xor_b32_e32 v208, 46, v247
	v_xor_b32_e32 v209, 45, v247
	v_xor_b32_e32 v210, 44, v247
	v_xor_b32_e32 v211, 39, v247
	v_xor_b32_e32 v212, 38, v247
	v_xor_b32_e32 v213, 37, v247
	v_xor_b32_e32 v214, 36, v247
	v_xor_b32_e32 v215, 31, v247
	v_xor_b32_e32 v216, 30, v247
	v_xor_b32_e32 v217, 29, v247
	v_xor_b32_e32 v218, 28, v247
	v_xor_b32_e32 v219, 23, v247
	v_xor_b32_e32 v220, 22, v247
	v_xor_b32_e32 v221, 21, v247
	v_xor_b32_e32 v222, 20, v247
	v_xor_b32_e32 v223, 15, v247
	v_xor_b32_e32 v224, 14, v247
	v_xor_b32_e32 v225, 13, v247
	v_xor_b32_e32 v226, 12, v247
	v_xor_b32_e32 v227, 7, v247
	v_xor_b32_e32 v228, 6, v247
	v_xor_b32_e32 v229, 5, v247
	v_xor_b32_e32 v230, 4, v247
	v_lshrrev_b32_e32 v243, 4, v242
	v_xor_b32_e32 v247, v243, v242
	v_lshlrev_b32_e32 v242, 4, v242
	v_and_b32_e32 v247, 15, v247
	v_lshlrev_b32_e32 v247, 4, v247
	v_lshl_or_b32 v243, v243, 8, v247
	v_mov_b32_e32 v244, 0xff800000
	v_mov_b32_e32 v247, 0x14000
	v_mov_b32_e32 v128, 0x20021001
	ds_write_b32 v247, v128 offset:0
	v_mov_b32_e32 v128, 0x40043003
	ds_write_b32 v247, v128 offset:4
	v_mov_b32_e32 v128, 0x60065005
	ds_write_b32 v247, v128 offset:8
	v_mov_b32_e32 v128, 0x80087007
	ds_write_b32 v247, v128 offset:12
	v_mov_b32_e32 v128, 0xa00a9009
	ds_write_b32 v247, v128 offset:16
	v_mov_b32_e32 v128, 0xc00cb00b
	ds_write_b32 v247, v128 offset:20
	v_mov_b32_e32 v128, 0xe00ed00d
	ds_write_b32 v247, v128 offset:24
	v_mov_b32_e32 v128, 0x2112f00f
	ds_write_b32 v247, v128 offset:28
	v_mov_b32_e32 v128, 0x41143113
	ds_write_b32 v247, v128 offset:32
	v_mov_b32_e32 v128, 0x61165115
	ds_write_b32 v247, v128 offset:36
	v_mov_b32_e32 v128, 0x32237117
	ds_write_b32 v247, v128 offset:40
	v_mov_b32_e32 v128, 0x4224
	ds_write_b32 v247, v128 offset:44
	v_mov_b32_e32 v128, 0x22221111
	ds_write_b32 v247, v128 offset:48
	v_mov_b32_e32 v128, 0x3333
	ds_write_b32 v247, v128 offset:52
	v_mov_b32_e32 v128, 0
	ds_write_b32 v247, v128 offset:56
	v_mov_b32_e32 v128, 0
	ds_write_b32 v247, v128 offset:60
	v_mov_b32_e32 v246, 0x14000
	s_and_b32 s25, s2, 7
	s_lshl_b32 s25, s25, 3
	s_bfe_u32 s26, s2, 0x30003
	s_add_i32 s25, s25, s26
	s_lshl_b32 s23, s25, 8
	s_lshl_b32 s26, s21, 5
	s_add_i32 s23, s23, s26
	s_lshr_b32 s24, s2, 6
	s_mov_b32 s22, 0
.Ltk0_unit:
	s_lshl_b32 s26, s24, 9
	s_mul_hi_u32 s17, s23, 0x1000
	s_lshl_b32 s16, s23, 12
	s_add_u32 s16, s16, s26
	s_addc_u32 s17, s17, 0
	s_add_u32 s16, s16, s8
	s_addc_u32 s17, s17, s9
	s_lshl_b32 s26, s24, 16
	s_add_u32 s18, s14, s26
	s_addc_u32 s19, s15, 0
	s_lshl_b32 s20, s23, 9
	s_lshl_b32 s26, s24, 6
	s_add_i32 s20, s20, s26
	s_add_u32 s28, s10, s20
	s_addc_u32 s29, s11, 0
	s_add_u32 s30, s12, s20
	s_addc_u32 s31, s13, 0
	s_barrier
	global_load_dwordx4 v[0:3], v242, s[18:19]
	v_add_u32_e32 v247, 0x2000, v242
	global_load_dwordx4 v[4:7], v247, s[18:19]
	v_add_u32_e32 v247, 0x4000, v242
	global_load_dwordx4 v[8:11], v247, s[18:19]
	v_add_u32_e32 v247, 0x6000, v242
	global_load_dwordx4 v[12:15], v247, s[18:19]
	v_add_u32_e32 v247, 0x8000, v242
	global_load_dwordx4 v[16:19], v247, s[18:19]
	v_add_u32_e32 v247, 0xa000, v242
	global_load_dwordx4 v[20:23], v247, s[18:19]
	v_add_u32_e32 v247, 0xc000, v242
	global_load_dwordx4 v[24:27], v247, s[18:19]
	v_add_u32_e32 v247, 0xe000, v242
	global_load_dwordx4 v[28:31], v247, s[18:19]
	global_load_dwordx4 v[64:67], v239, s[16:17] offset:0
	global_load_dwordx4 v[68:71], v239, s[16:17] offset:32
	global_load_dwordx4 v[72:75], v239, s[16:17] offset:64
	global_load_dwordx4 v[76:79], v239, s[16:17] offset:96
	global_load_dwordx4 v[80:83], v239, s[16:17] offset:128
	global_load_dwordx4 v[84:87], v239, s[16:17] offset:160
	global_load_dwordx4 v[88:91], v239, s[16:17] offset:192
	global_load_dwordx4 v[92:95], v239, s[16:17] offset:224
	s_waitcnt vmcnt(15)
	ds_write_b128 v243, v[0:3] offset:0
	s_waitcnt vmcnt(14)
	ds_write_b128 v243, v[4:7] offset:8192
	s_waitcnt vmcnt(13)
	ds_write_b128 v243, v[8:11] offset:16384
	s_waitcnt vmcnt(12)
	ds_write_b128 v243, v[12:15] offset:24576
	s_waitcnt vmcnt(11)
	ds_write_b128 v243, v[16:19] offset:32768
	s_waitcnt vmcnt(10)
	ds_write_b128 v243, v[20:23] offset:40960
	s_waitcnt vmcnt(9)
	ds_write_b128 v243, v[24:27] offset:49152
	s_waitcnt vmcnt(8)
	ds_write_b128 v243, v[28:31] offset:57344
	s_waitcnt lgkmcnt(0)
	s_barrier
	ds_read_b128 v[96:99], v231 offset:0
	ds_read_b128 v[100:103], v232 offset:0
	ds_read_b128 v[104:107], v233 offset:0
	ds_read_b128 v[108:111], v234 offset:0
	ds_read_b128 v[112:115], v235 offset:0
	ds_read_b128 v[116:119], v236 offset:0
	ds_read_b128 v[120:123], v237 offset:0
	ds_read_b128 v[124:127], v238 offset:0
	s_waitcnt vmcnt(0)
	s_waitcnt lgkmcnt(4)
	v_mfma_f32_32x32x16_bf16 v[0:15], v[96:99], v[64:67], 0
	v_mfma_f32_32x32x16_bf16 v[0:15], v[100:103], v[68:71], v[0:15]
	v_mfma_f32_32x32x16_bf16 v[0:15], v[104:107], v[72:75], v[0:15]
	v_mfma_f32_32x32x16_bf16 v[0:15], v[108:111], v[76:79], v[0:15]
	ds_read_b128 v[96:99], v231 offset:8192
	ds_read_b128 v[100:103], v232 offset:8192
	ds_read_b128 v[104:107], v233 offset:8192
	ds_read_b128 v[108:111], v234 offset:8192
	s_waitcnt lgkmcnt(4)
	v_mfma_f32_32x32x16_bf16 v[0:15], v[112:115], v[80:83], v[0:15]
	v_mfma_f32_32x32x16_bf16 v[0:15], v[116:119], v[84:87], v[0:15]
	v_mfma_f32_32x32x16_bf16 v[0:15], v[120:123], v[88:91], v[0:15]
	v_mfma_f32_32x32x16_bf16 v[0:15], v[124:127], v[92:95], v[0:15]
	ds_read_b128 v[112:115], v235 offset:8192
	ds_read_b128 v[116:119], v236 offset:8192
	ds_read_b128 v[120:123], v237 offset:8192
	ds_read_b128 v[124:127], v238 offset:8192
	s_waitcnt lgkmcnt(4)
	v_mfma_f32_32x32x16_bf16 v[16:31], v[96:99], v[64:67], 0
	v_mfma_f32_32x32x16_bf16 v[16:31], v[100:103], v[68:71], v[16:31]
	v_mfma_f32_32x32x16_bf16 v[16:31], v[104:107], v[72:75], v[16:31]
	v_mfma_f32_32x32x16_bf16 v[16:31], v[108:111], v[76:79], v[16:31]
	ds_read_b128 v[96:99], v231 offset:16384
	ds_read_b128 v[100:103], v232 offset:16384
	ds_read_b128 v[104:107], v233 offset:16384
	ds_read_b128 v[108:111], v234 offset:16384
	s_waitcnt lgkmcnt(4)
	v_mfma_f32_32x32x16_bf16 v[16:31], v[112:115], v[80:83], v[16:31]
	v_mfma_f32_32x32x16_bf16 v[16:31], v[116:119], v[84:87], v[16:31]
	v_mfma_f32_32x32x16_bf16 v[16:31], v[120:123], v[88:91], v[16:31]
	v_mfma_f32_32x32x16_bf16 v[16:31], v[124:127], v[92:95], v[16:31]
	ds_read_b128 v[112:115], v235 offset:16384
	ds_read_b128 v[116:119], v236 offset:16384
	ds_read_b128 v[120:123], v237 offset:16384
	ds_read_b128 v[124:127], v238 offset:16384
	s_waitcnt lgkmcnt(4)
	v_mfma_f32_32x32x16_bf16 v[32:47], v[96:99], v[64:67], 0
	v_mfma_f32_32x32x16_bf16 v[32:47], v[100:103], v[68:71], v[32:47]
	v_mfma_f32_32x32x16_bf16 v[32:47], v[104:107], v[72:75], v[32:47]
	v_mfma_f32_32x32x16_bf16 v[32:47], v[108:111], v[76:79], v[32:47]
	ds_read_b128 v[96:99], v231 offset:24576
	ds_read_b128 v[100:103], v232 offset:24576
	ds_read_b128 v[104:107], v233 offset:24576
	ds_read_b128 v[108:111], v234 offset:24576
	s_waitcnt lgkmcnt(4)
	v_mfma_f32_32x32x16_bf16 v[32:47], v[112:115], v[80:83], v[32:47]
	v_mfma_f32_32x32x16_bf16 v[32:47], v[116:119], v[84:87], v[32:47]
	v_mfma_f32_32x32x16_bf16 v[32:47], v[120:123], v[88:91], v[32:47]
	v_mfma_f32_32x32x16_bf16 v[32:47], v[124:127], v[92:95], v[32:47]
	ds_read_b128 v[112:115], v235 offset:24576
	ds_read_b128 v[116:119], v236 offset:24576
	ds_read_b128 v[120:123], v237 offset:24576
	ds_read_b128 v[124:127], v238 offset:24576
	s_waitcnt lgkmcnt(4)
	v_mfma_f32_32x32x16_bf16 v[48:63], v[96:99], v[64:67], 0
	v_mfma_f32_32x32x16_bf16 v[48:63], v[100:103], v[68:71], v[48:63]
	v_mfma_f32_32x32x16_bf16 v[48:63], v[104:107], v[72:75], v[48:63]
	v_mfma_f32_32x32x16_bf16 v[48:63], v[108:111], v[76:79], v[48:63]
	s_waitcnt lgkmcnt(0)
	v_mfma_f32_32x32x16_bf16 v[48:63], v[112:115], v[80:83], v[48:63]
	v_mfma_f32_32x32x16_bf16 v[48:63], v[116:119], v[84:87], v[48:63]
	v_mfma_f32_32x32x16_bf16 v[48:63], v[120:123], v[88:91], v[48:63]
	v_mfma_f32_32x32x16_bf16 v[48:63], v[124:127], v[92:95], v[48:63]
	global_load_dwordx4 v[64:67], v239, s[16:17] offset:256
	global_load_dwordx4 v[68:71], v239, s[16:17] offset:288
	global_load_dwordx4 v[72:75], v239, s[16:17] offset:320
	global_load_dwordx4 v[76:79], v239, s[16:17] offset:352
	global_load_dwordx4 v[80:83], v239, s[16:17] offset:384
	global_load_dwordx4 v[84:87], v239, s[16:17] offset:416
	global_load_dwordx4 v[88:91], v239, s[16:17] offset:448
	global_load_dwordx4 v[92:95], v239, s[16:17] offset:480
	s_nop 11
	v_and_or_b32 v0, v0, s6, v160
	v_and_or_b32 v1, v1, s6, v161
	v_and_or_b32 v2, v2, s6, v162
	v_and_or_b32 v3, v3, s6, v163
	v_and_or_b32 v4, v4, s6, v164
	v_and_or_b32 v5, v5, s6, v165
	v_and_or_b32 v6, v6, s6, v166
	v_and_or_b32 v7, v7, s6, v167
	v_and_or_b32 v8, v8, s6, v168
	v_and_or_b32 v9, v9, s6, v169
	v_and_or_b32 v10, v10, s6, v170
	v_and_or_b32 v11, v11, s6, v171
	v_and_or_b32 v12, v12, s6, v172
	v_and_or_b32 v13, v13, s6, v173
	v_and_or_b32 v14, v14, s6, v174
	v_and_or_b32 v15, v15, s6, v175
	v_and_or_b32 v16, v16, s6, v176
	v_and_or_b32 v17, v17, s6, v177
	v_and_or_b32 v18, v18, s6, v178
	v_and_or_b32 v19, v19, s6, v179
	v_and_or_b32 v20, v20, s6, v180
	v_and_or_b32 v21, v21, s6, v181
	v_and_or_b32 v22, v22, s6, v182
	v_and_or_b32 v23, v23, s6, v183
	v_and_or_b32 v24, v24, s6, v184
	v_and_or_b32 v25, v25, s6, v185
	v_and_or_b32 v26, v26, s6, v186
	v_and_or_b32 v27, v27, s6, v187
	v_and_or_b32 v28, v28, s6, v188
	v_and_or_b32 v29, v29, s6, v189
	v_and_or_b32 v30, v30, s6, v190
	v_and_or_b32 v31, v31, s6, v191
	v_and_or_b32 v32, v32, s6, v192
	v_and_or_b32 v33, v33, s6, v193
	v_and_or_b32 v34, v34, s6, v194
	v_and_or_b32 v35, v35, s6, v195
	v_and_or_b32 v36, v36, s6, v196
	v_and_or_b32 v37, v37, s6, v204
	v_and_or_b32 v38, v38, s6, v205
	v_and_or_b32 v39, v39, s6, v206
	v_and_or_b32 v40, v40, s6, v207
	v_and_or_b32 v41, v41, s6, v208
	v_and_or_b32 v42, v42, s6, v209
	v_and_or_b32 v43, v43, s6, v210
	v_and_or_b32 v44, v44, s6, v211
	v_and_or_b32 v45, v45, s6, v212
	v_and_or_b32 v46, v46, s6, v213
	v_and_or_b32 v47, v47, s6, v214
	v_and_or_b32 v48, v48, s6, v215
	v_and_or_b32 v49, v49, s6, v216
	v_and_or_b32 v50, v50, s6, v217
	v_and_or_b32 v51, v51, s6, v218
	v_and_or_b32 v52, v52, s6, v219
	v_and_or_b32 v53, v53, s6, v220
	v_and_or_b32 v54, v54, s6, v221
	v_and_or_b32 v55, v55, s6, v222
	v_and_or_b32 v56, v56, s6, v223
	v_and_or_b32 v57, v57, s6, v224
	v_and_or_b32 v58, v58, s6, v225
	v_and_or_b32 v59, v59, s6, v226
	v_and_or_b32 v60, v60, s6, v227
	v_and_or_b32 v61, v61, s6, v228
	v_and_or_b32 v62, v62, s6, v229
	v_and_or_b32 v63, v63, s6, v230
	v_max_f32_e32 v144, v0, v13
	v_min_f32_e32 v13, v0, v13
	v_max_f32_e32 v145, v1, v12
	v_min_f32_e32 v12, v1, v12
	v_max_f32_e32 v146, v2, v15
	v_min_f32_e32 v15, v2, v15
	v_max_f32_e32 v147, v3, v14
	v_min_f32_e32 v14, v3, v14
	v_max_f32_e32 v148, v4, v8
	v_min_f32_e32 v8, v4, v8
	v_max_f32_e32 v149, v5, v6
	v_min_f32_e32 v6, v5, v6
	v_max_f32_e32 v150, v7, v11
	v_min_f32_e32 v11, v7, v11
	v_max_f32_e32 v151, v9, v10
	v_min_f32_e32 v10, v9, v10
	v_max_f32_e32 v249, v144, v149
	v_min_f32_e32 v149, v144, v149
	v_max_f32_e32 v250, v145, v150
	v_min_f32_e32 v150, v145, v150
	v_max_f32_e32 v251, v146, v151
	v_min_f32_e32 v151, v146, v151
	v_max_f32_e32 v252, v147, v148
	v_min_f32_e32 v148, v147, v148
	v_max_f32_e32 v253, v6, v13
	v_min_f32_e32 v13, v6, v13
	v_max_f32_e32 v254, v8, v14
	v_min_f32_e32 v14, v8, v14
	v_max_f32_e32 v255, v10, v15
	v_min_f32_e32 v15, v10, v15
	v_max_f32_e32 v96, v11, v12
	v_min_f32_e32 v12, v11, v12
	v_max_f32_e32 v97, v249, v250
	v_min_f32_e32 v250, v249, v250
	v_max_f32_e32 v98, v251, v252
	v_min_f32_e32 v252, v251, v252
	v_max_f32_e32 v99, v148, v149
	v_min_f32_e32 v149, v148, v149
	v_max_f32_e32 v100, v253, v254
	v_min_f32_e32 v254, v253, v254
	v_max_f32_e32 v101, v150, v151
	v_min_f32_e32 v151, v150, v151
	v_max_f32_e32 v102, v255, v96
	v_min_f32_e32 v96, v255, v96
	v_max_f32_e32 v103, v12, v13
	v_min_f32_e32 v13, v12, v13
	v_max_f32_e32 v104, v14, v15
	v_min_f32_e32 v15, v14, v15
	v_max_f32_e32 v105, v97, v98
	v_min_f32_e32 v98, v97, v98
	v_max_f32_e32 v106, v250, v252
	v_min_f32_e32 v252, v250, v252
	v_max_f32_e32 v107, v99, v102
	v_min_f32_e32 v102, v99, v102
	v_max_f32_e32 v108, v149, v96
	v_min_f32_e32 v96, v149, v96
	v_max_f32_e32 v109, v100, v101
	v_min_f32_e32 v101, v100, v101
	v_max_f32_e32 v110, v254, v151
	v_min_f32_e32 v151, v254, v151
	v_max_f32_e32 v111, v103, v104
	v_min_f32_e32 v104, v103, v104
	v_max_f32_e32 v112, v13, v15
	v_min_f32_e32 v15, v13, v15
	v_max_f32_e32 v113, v106, v98
	v_min_f32_e32 v98, v106, v98
	v_max_f32_e32 v114, v252, v111
	v_min_f32_e32 v111, v252, v111
	v_max_f32_e32 v115, v107, v109
	v_min_f32_e32 v109, v107, v109
	v_max_f32_e32 v116, v108, v101
	v_min_f32_e32 v101, v108, v101
	v_max_f32_e32 v117, v110, v102
	v_min_f32_e32 v102, v110, v102
	v_max_f32_e32 v118, v151, v96
	v_min_f32_e32 v96, v151, v96
	v_max_f32_e32 v119, v112, v104
	v_min_f32_e32 v104, v112, v104
	v_max_f32_e32 v120, v113, v115
	v_min_f32_e32 v115, v113, v115
	v_max_f32_e32 v121, v98, v109
	v_min_f32_e32 v109, v98, v109
	v_max_f32_e32 v122, v116, v117
	v_min_f32_e32 v117, v116, v117
	v_max_f32_e32 v123, v101, v102
	v_min_f32_e32 v102, v101, v102
	v_max_f32_e32 v124, v118, v119
	v_min_f32_e32 v119, v118, v119
	v_max_f32_e32 v125, v96, v104
	v_min_f32_e32 v104, v96, v104
	v_max_f32_e32 v126, v121, v115
	v_min_f32_e32 v115, v121, v115
	v_max_f32_e32 v127, v114, v109
	v_min_f32_e32 v109, v114, v109
	v_max_f32_e32 v0, v124, v111
	v_min_f32_e32 v111, v124, v111
	v_max_f32_e32 v1, v125, v119
	v_min_f32_e32 v119, v125, v119
	v_max_f32_e32 v2, v127, v122
	v_min_f32_e32 v122, v127, v122
	v_max_f32_e32 v3, v109, v117
	v_min_f32_e32 v117, v109, v117
	v_max_f32_e32 v4, v123, v0
	v_min_f32_e32 v0, v123, v0
	v_max_f32_e32 v5, v102, v111
	v_min_f32_e32 v111, v102, v111
	v_max_f32_e32 v7, v2, v115
	v_min_f32_e32 v115, v2, v115
	v_max_f32_e32 v9, v122, v3
	v_min_f32_e32 v3, v122, v3
	v_max_f32_e32 v144, v4, v117
	v_min_f32_e32 v117, v4, v117
	v_max_f32_e32 v145, v0, v5
	v_min_f32_e32 v5, v0, v5
	v_max_f32_e32 v146, v1, v111
	v_min_f32_e32 v111, v1, v111
	v_max_f32_e32 v147, v3, v144
	v_min_f32_e32 v144, v3, v144
	v_max_f32_e32 v6, v117, v145
	v_min_f32_e32 v145, v117, v145
	v_max_f32_e32 v8, v16, v29
	v_min_f32_e32 v29, v16, v29
	v_max_f32_e32 v10, v17, v28
	v_min_f32_e32 v28, v17, v28
	v_max_f32_e32 v11, v18, v31
	v_min_f32_e32 v31, v18, v31
	v_max_f32_e32 v249, v19, v30
	v_min_f32_e32 v30, v19, v30
	v_max_f32_e32 v251, v20, v24
	v_min_f32_e32 v24, v20, v24
	v_max_f32_e32 v148, v21, v22
	v_min_f32_e32 v22, v21, v22
	v_max_f32_e32 v253, v23, v27
	v_min_f32_e32 v27, v23, v27
	v_max_f32_e32 v150, v25, v26
	v_min_f32_e32 v26, v25, v26
	v_max_f32_e32 v255, v8, v148
	v_min_f32_e32 v148, v8, v148
	v_max_f32_e32 v12, v10, v253
	v_min_f32_e32 v253, v10, v253
	v_max_f32_e32 v14, v11, v150
	v_min_f32_e32 v150, v11, v150
	v_max_f32_e32 v97, v249, v251
	v_min_f32_e32 v251, v249, v251
	v_max_f32_e32 v250, v22, v29
	v_min_f32_e32 v29, v22, v29
	v_max_f32_e32 v99, v24, v30
	v_min_f32_e32 v30, v24, v30
	v_max_f32_e32 v149, v26, v31
	v_min_f32_e32 v31, v26, v31
	v_max_f32_e32 v100, v27, v28
	v_min_f32_e32 v28, v27, v28
	v_max_f32_e32 v254, v255, v12
	v_min_f32_e32 v12, v255, v12
	v_max_f32_e32 v103, v14, v97
	v_min_f32_e32 v97, v14, v97
	v_max_f32_e32 v13, v251, v148
	v_min_f32_e32 v148, v251, v148
	v_max_f32_e32 v106, v250, v99
	v_min_f32_e32 v99, v250, v99
	v_max_f32_e32 v252, v253, v150
	v_min_f32_e32 v150, v253, v150
	v_max_f32_e32 v107, v149, v100
	v_min_f32_e32 v100, v149, v100
	v_max_f32_e32 v108, v28, v29
	v_min_f32_e32 v29, v28, v29
	v_max_f32_e32 v110, v30, v31
	v_min_f32_e32 v31, v30, v31
	v_max_f32_e32 v151, v254, v103
	v_min_f32_e32 v103, v254, v103
	v_max_f32_e32 v112, v12, v97
	v_min_f32_e32 v97, v12, v97
	v_max_f32_e32 v113, v13, v107
	v_min_f32_e32 v107, v13, v107
	v_max_f32_e32 v98, v148, v100
	v_min_f32_e32 v100, v148, v100
	v_max_f32_e32 v116, v106, v252
	v_min_f32_e32 v252, v106, v252
	v_max_f32_e32 v101, v99, v150
	v_min_f32_e32 v150, v99, v150
	v_max_f32_e32 v118, v108, v110
	v_min_f32_e32 v110, v108, v110
	v_max_f32_e32 v96, v29, v31
	v_min_f32_e32 v31, v29, v31
	v_max_f32_e32 v121, v112, v103
	v_min_f32_e32 v103, v112, v103
	v_max_f32_e32 v114, v97, v118
	v_min_f32_e32 v118, v97, v118
	v_max_f32_e32 v124, v113, v116
	v_min_f32_e32 v116, v113, v116
	v_max_f32_e32 v125, v98, v252
	v_min_f32_e32 v252, v98, v252
	v_max_f32_e32 v127, v101, v107
	v_min_f32_e32 v107, v101, v107
	v_max_f32_e32 v109, v150, v100
	v_min_f32_e32 v100, v150, v100
	v_max_f32_e32 v123, v96, v110
	v_min_f32_e32 v110, v96, v110
	v_max_f32_e32 v102, v121, v124
	v_min_f32_e32 v124, v121, v124
	v_max_f32_e32 v2, v103, v116
	v_min_f32_e32 v116, v103, v116
	v_max_f32_e32 v122, v125, v127
	v_min_f32_e32 v127, v125, v127
	v_max_f32_e32 v4, v252, v107
	v_min_f32_e32 v107, v252, v107
	v_max_f32_e32 v0, v109, v123
	v_min_f32_e32 v123, v109, v123
	v_max_f32_e32 v1, v100, v110
	v_min_f32_e32 v110, v100, v110
	v_max_f32_e32 v3, v2, v124
	v_min_f32_e32 v124, v2, v124
	v_max_f32_e32 v117, v114, v116
	v_min_f32_e32 v116, v114, v116
	v_max_f32_e32 v16, v0, v118
	v_min_f32_e32 v118, v0, v118
	v_max_f32_e32 v17, v1, v123
	v_min_f32_e32 v123, v1, v123
	v_max_f32_e32 v18, v117, v122
	v_min_f32_e32 v122, v117, v122
	v_max_f32_e32 v19, v116, v127
	v_min_f32_e32 v127, v116, v127
	v_max_f32_e32 v20, v4, v16
	v_min_f32_e32 v16, v4, v16
	v_max_f32_e32 v21, v107, v118
	v_min_f32_e32 v118, v107, v118
	v_max_f32_e32 v23, v18, v124
	v_min_f32_e32 v124, v18, v124
	v_max_f32_e32 v25, v122, v19
	v_min_f32_e32 v19, v122, v19
	v_max_f32_e32 v8, v20, v127
	v_min_f32_e32 v127, v20, v127
	v_max_f32_e32 v10, v16, v21
	v_min_f32_e32 v21, v16, v21
	v_max_f32_e32 v11, v17, v118
	v_min_f32_e32 v118, v17, v118
	v_max_f32_e32 v249, v19, v8
	v_min_f32_e32 v8, v19, v8
	v_max_f32_e32 v22, v127, v10
	v_min_f32_e32 v10, v127, v10
	v_max_f32_e32 v24, v32, v45
	v_min_f32_e32 v45, v32, v45
	v_max_f32_e32 v26, v33, v44
	v_min_f32_e32 v44, v33, v44
	v_max_f32_e32 v27, v34, v47
	v_min_f32_e32 v47, v34, v47
	v_max_f32_e32 v255, v35, v46
	v_min_f32_e32 v46, v35, v46
	v_max_f32_e32 v14, v36, v40
	v_min_f32_e32 v40, v36, v40
	v_max_f32_e32 v251, v37, v38
	v_min_f32_e32 v38, v37, v38
	v_max_f32_e32 v250, v39, v43
	v_min_f32_e32 v43, v39, v43
	v_max_f32_e32 v253, v41, v42
	v_min_f32_e32 v42, v41, v42
	v_max_f32_e32 v149, v24, v251
	v_min_f32_e32 v251, v24, v251
	v_max_f32_e32 v28, v26, v250
	v_min_f32_e32 v250, v26, v250
	v_max_f32_e32 v30, v27, v253
	v_min_f32_e32 v253, v27, v253
	v_max_f32_e32 v254, v255, v14
	v_min_f32_e32 v14, v255, v14
	v_max_f32_e32 v12, v38, v45
	v_min_f32_e32 v45, v38, v45
	v_max_f32_e32 v13, v40, v46
	v_min_f32_e32 v46, v40, v46
	v_max_f32_e32 v148, v42, v47
	v_min_f32_e32 v47, v42, v47
	v_max_f32_e32 v106, v43, v44
	v_min_f32_e32 v44, v43, v44
	v_max_f32_e32 v99, v149, v28
	v_min_f32_e32 v28, v149, v28
	v_max_f32_e32 v108, v30, v254
	v_min_f32_e32 v254, v30, v254
	v_max_f32_e32 v29, v14, v251
	v_min_f32_e32 v251, v14, v251
	v_max_f32_e32 v112, v12, v13
	v_min_f32_e32 v13, v12, v13
	v_max_f32_e32 v97, v250, v253
	v_min_f32_e32 v253, v250, v253
	v_max_f32_e32 v113, v148, v106
	v_min_f32_e32 v106, v148, v106
	v_max_f32_e32 v98, v44, v45
	v_min_f32_e32 v45, v44, v45
	v_max_f32_e32 v101, v46, v47
	v_min_f32_e32 v47, v46, v47
	v_max_f32_e32 v150, v99, v108
	v_min_f32_e32 v108, v99, v108
	v_max_f32_e32 v96, v28, v254
	v_min_f32_e32 v254, v28, v254
	v_max_f32_e32 v121, v29, v113
	v_min_f32_e32 v113, v29, v113
	v_max_f32_e32 v103, v251, v106
	v_min_f32_e32 v106, v251, v106
	v_max_f32_e32 v125, v112, v97
	v_min_f32_e32 v97, v112, v97
	v_max_f32_e32 v252, v13, v253
	v_min_f32_e32 v253, v13, v253
	v_max_f32_e32 v109, v98, v101
	v_min_f32_e32 v101, v98, v101
	v_max_f32_e32 v100, v45, v47
	v_min_f32_e32 v47, v45, v47
	v_max_f32_e32 v2, v96, v108
	v_min_f32_e32 v108, v96, v108
	v_max_f32_e32 v114, v254, v109
	v_min_f32_e32 v109, v254, v109
	v_max_f32_e32 v0, v121, v125
	v_min_f32_e32 v125, v121, v125
	v_max_f32_e32 v1, v103, v97
	v_min_f32_e32 v97, v103, v97
	v_max_f32_e32 v117, v252, v113
	v_min_f32_e32 v113, v252, v113
	v_max_f32_e32 v116, v253, v106
	v_min_f32_e32 v106, v253, v106
	v_max_f32_e32 v4, v100, v101
	v_min_f32_e32 v101, v100, v101
	v_max_f32_e32 v107, v2, v0
	v_min_f32_e32 v0, v2, v0
	v_max_f32_e32 v18, v108, v125
	v_min_f32_e32 v125, v108, v125
	v_max_f32_e32 v122, v1, v117
	v_min_f32_e32 v117, v1, v117
	v_max_f32_e32 v20, v97, v113
	v_min_f32_e32 v113, v97, v113
	v_max_f32_e32 v16, v116, v4
	v_min_f32_e32 v4, v116, v4
	v_max_f32_e32 v17, v106, v101
	v_min_f32_e32 v101, v106, v101
	v_max_f32_e32 v19, v18, v0
	v_min_f32_e32 v0, v18, v0
	v_max_f32_e32 v127, v114, v125
	v_min_f32_e32 v125, v114, v125
	v_max_f32_e32 v32, v16, v109
	v_min_f32_e32 v109, v16, v109
	v_max_f32_e32 v33, v17, v4
	v_min_f32_e32 v4, v17, v4
	v_max_f32_e32 v34, v127, v122
	v_min_f32_e32 v122, v127, v122
	v_max_f32_e32 v35, v125, v117
	v_min_f32_e32 v117, v125, v117
	v_max_f32_e32 v36, v20, v32
	v_min_f32_e32 v32, v20, v32
	v_max_f32_e32 v37, v113, v109
	v_min_f32_e32 v109, v113, v109
	v_max_f32_e32 v39, v34, v0
	v_min_f32_e32 v0, v34, v0
	v_max_f32_e32 v41, v122, v35
	v_min_f32_e32 v35, v122, v35
	v_max_f32_e32 v24, v36, v117
	v_min_f32_e32 v117, v36, v117
	v_max_f32_e32 v26, v32, v37
	v_min_f32_e32 v37, v32, v37
	v_max_f32_e32 v27, v33, v109
	v_min_f32_e32 v109, v33, v109
	v_max_f32_e32 v255, v35, v24
	v_min_f32_e32 v24, v35, v24
	v_max_f32_e32 v38, v117, v26
	v_min_f32_e32 v26, v117, v26
	v_max_f32_e32 v40, v48, v61
	v_min_f32_e32 v61, v48, v61
	v_max_f32_e32 v42, v49, v60
	v_min_f32_e32 v60, v49, v60
	v_max_f32_e32 v43, v50, v63
	v_min_f32_e32 v63, v50, v63
	v_max_f32_e32 v149, v51, v62
	v_min_f32_e32 v62, v51, v62
	v_max_f32_e32 v30, v52, v56
	v_min_f32_e32 v56, v52, v56
	v_max_f32_e32 v14, v53, v54
	v_min_f32_e32 v54, v53, v54
	v_max_f32_e32 v12, v55, v59
	v_min_f32_e32 v59, v55, v59
	v_max_f32_e32 v250, v57, v58
	v_min_f32_e32 v58, v57, v58
	v_max_f32_e32 v148, v40, v14
	v_min_f32_e32 v14, v40, v14
	v_max_f32_e32 v44, v42, v12
	v_min_f32_e32 v12, v42, v12
	v_max_f32_e32 v46, v43, v250
	v_min_f32_e32 v250, v43, v250
	v_max_f32_e32 v99, v149, v30
	v_min_f32_e32 v30, v149, v30
	v_max_f32_e32 v28, v54, v61
	v_min_f32_e32 v61, v54, v61
	v_max_f32_e32 v29, v56, v62
	v_min_f32_e32 v62, v56, v62
	v_max_f32_e32 v251, v58, v63
	v_min_f32_e32 v63, v58, v63
	v_max_f32_e32 v112, v59, v60
	v_min_f32_e32 v60, v59, v60
	v_max_f32_e32 v13, v148, v44
	v_min_f32_e32 v44, v148, v44
	v_max_f32_e32 v98, v46, v99
	v_min_f32_e32 v99, v46, v99
	v_max_f32_e32 v45, v30, v14
	v_min_f32_e32 v14, v30, v14
	v_max_f32_e32 v96, v28, v29
	v_min_f32_e32 v29, v28, v29
	v_max_f32_e32 v254, v12, v250
	v_min_f32_e32 v250, v12, v250
	v_max_f32_e32 v121, v251, v112
	v_min_f32_e32 v112, v251, v112
	v_max_f32_e32 v103, v60, v61
	v_min_f32_e32 v61, v60, v61
	v_max_f32_e32 v252, v62, v63
	v_min_f32_e32 v63, v62, v63
	v_max_f32_e32 v253, v13, v98
	v_min_f32_e32 v98, v13, v98
	v_max_f32_e32 v100, v44, v99
	v_min_f32_e32 v99, v44, v99
	v_max_f32_e32 v2, v45, v121
	v_min_f32_e32 v121, v45, v121
	v_max_f32_e32 v108, v14, v112
	v_min_f32_e32 v112, v14, v112
	v_max_f32_e32 v1, v96, v254
	v_min_f32_e32 v254, v96, v254
	v_max_f32_e32 v97, v29, v250
	v_min_f32_e32 v250, v29, v250
	v_max_f32_e32 v116, v103, v252
	v_min_f32_e32 v252, v103, v252
	v_max_f32_e32 v106, v61, v63
	v_min_f32_e32 v63, v61, v63
	v_max_f32_e32 v18, v100, v98
	v_min_f32_e32 v98, v100, v98
	v_max_f32_e32 v114, v99, v116
	v_min_f32_e32 v116, v99, v116
	v_max_f32_e32 v16, v2, v1
	v_min_f32_e32 v1, v2, v1
	v_max_f32_e32 v17, v108, v254
	v_min_f32_e32 v254, v108, v254
	v_max_f32_e32 v127, v97, v121
	v_min_f32_e32 v121, v97, v121
	v_max_f32_e32 v125, v250, v112
	v_min_f32_e32 v112, v250, v112
	v_max_f32_e32 v20, v106, v252
	v_min_f32_e32 v252, v106, v252
	v_max_f32_e32 v113, v18, v16
	v_min_f32_e32 v16, v18, v16
	v_max_f32_e32 v34, v98, v1
	v_min_f32_e32 v1, v98, v1
	v_max_f32_e32 v122, v17, v127
	v_min_f32_e32 v127, v17, v127
	v_max_f32_e32 v36, v254, v121
	v_min_f32_e32 v121, v254, v121
	v_max_f32_e32 v32, v125, v20
	v_min_f32_e32 v20, v125, v20
	v_max_f32_e32 v33, v112, v252
	v_min_f32_e32 v252, v112, v252
	v_max_f32_e32 v35, v34, v16
	v_min_f32_e32 v16, v34, v16
	v_max_f32_e32 v117, v114, v1
	v_min_f32_e32 v1, v114, v1
	v_max_f32_e32 v48, v32, v116
	v_min_f32_e32 v116, v32, v116
	v_max_f32_e32 v49, v33, v20
	v_min_f32_e32 v20, v33, v20
	v_max_f32_e32 v50, v117, v122
	v_min_f32_e32 v122, v117, v122
	v_max_f32_e32 v51, v1, v127
	v_min_f32_e32 v127, v1, v127
	v_max_f32_e32 v52, v36, v48
	v_min_f32_e32 v48, v36, v48
	v_max_f32_e32 v53, v121, v116
	v_min_f32_e32 v116, v121, v116
	v_max_f32_e32 v55, v50, v16
	v_min_f32_e32 v16, v50, v16
	v_max_f32_e32 v57, v122, v51
	v_min_f32_e32 v51, v122, v51
	v_max_f32_e32 v40, v52, v127
	v_min_f32_e32 v127, v52, v127
	v_max_f32_e32 v42, v48, v53
	v_min_f32_e32 v53, v48, v53
	v_max_f32_e32 v43, v49, v116
	v_min_f32_e32 v116, v49, v116
	v_max_f32_e32 v149, v51, v40
	v_min_f32_e32 v40, v51, v40
	v_max_f32_e32 v54, v127, v42
	v_min_f32_e32 v42, v127, v42
	v_max_f32_e32 v105, v105, v31
	v_max_f32_e32 v120, v120, v110
	v_max_f32_e32 v126, v126, v123
	v_max_f32_e32 v7, v7, v118
	v_max_f32_e32 v115, v115, v11
	v_max_f32_e32 v9, v9, v21
	v_max_f32_e32 v147, v147, v10
	v_max_f32_e32 v144, v144, v22
	v_max_f32_e32 v6, v6, v8
	v_max_f32_e32 v145, v145, v249
	v_max_f32_e32 v5, v5, v25
	v_max_f32_e32 v146, v146, v124
	v_max_f32_e32 v111, v111, v23
	v_max_f32_e32 v119, v119, v3
	v_max_f32_e32 v104, v104, v102
	v_max_f32_e32 v15, v15, v151
	v_max_f32_e32 v56, v105, v6
	v_min_f32_e32 v6, v105, v6
	v_max_f32_e32 v58, v120, v145
	v_min_f32_e32 v145, v120, v145
	v_max_f32_e32 v59, v126, v5
	v_min_f32_e32 v5, v126, v5
	v_max_f32_e32 v148, v7, v146
	v_min_f32_e32 v146, v7, v146
	v_max_f32_e32 v46, v115, v111
	v_min_f32_e32 v111, v115, v111
	v_max_f32_e32 v30, v9, v119
	v_min_f32_e32 v119, v9, v119
	v_max_f32_e32 v28, v147, v104
	v_min_f32_e32 v104, v147, v104
	v_max_f32_e32 v12, v144, v15
	v_min_f32_e32 v15, v144, v15
	v_max_f32_e32 v251, v56, v46
	v_min_f32_e32 v46, v56, v46
	v_max_f32_e32 v60, v58, v30
	v_min_f32_e32 v30, v58, v30
	v_max_f32_e32 v62, v59, v28
	v_min_f32_e32 v28, v59, v28
	v_max_f32_e32 v13, v148, v12
	v_min_f32_e32 v12, v148, v12
	v_max_f32_e32 v44, v6, v111
	v_min_f32_e32 v111, v6, v111
	v_max_f32_e32 v45, v145, v119
	v_min_f32_e32 v119, v145, v119
	v_max_f32_e32 v14, v5, v104
	v_min_f32_e32 v104, v5, v104
	v_max_f32_e32 v96, v146, v15
	v_min_f32_e32 v15, v146, v15
	v_max_f32_e32 v29, v251, v62
	v_min_f32_e32 v62, v251, v62
	v_max_f32_e32 v103, v60, v13
	v_min_f32_e32 v13, v60, v13
	v_max_f32_e32 v61, v46, v28
	v_min_f32_e32 v28, v46, v28
	v_max_f32_e32 v100, v30, v12
	v_min_f32_e32 v12, v30, v12
	v_max_f32_e32 v99, v44, v14
	v_min_f32_e32 v14, v44, v14
	v_max_f32_e32 v2, v45, v96
	v_min_f32_e32 v96, v45, v96
	v_max_f32_e32 v108, v111, v104
	v_min_f32_e32 v104, v111, v104
	v_max_f32_e32 v97, v119, v15
	v_min_f32_e32 v15, v119, v15
	v_max_f32_e32 v250, v29, v103
	v_min_f32_e32 v103, v29, v103
	v_max_f32_e32 v106, v62, v13
	v_min_f32_e32 v13, v62, v13
	v_max_f32_e32 v18, v61, v100
	v_min_f32_e32 v100, v61, v100
	v_max_f32_e32 v98, v28, v12
	v_min_f32_e32 v12, v28, v12
	v_max_f32_e32 v17, v99, v2
	v_min_f32_e32 v2, v99, v2
	v_max_f32_e32 v254, v14, v96
	v_min_f32_e32 v96, v14, v96
	v_max_f32_e32 v125, v108, v97
	v_min_f32_e32 v97, v108, v97
	v_max_f32_e32 v112, v104, v15
	v_min_f32_e32 v15, v104, v15
	v_max_f32_e32 v150, v150, v63
	v_max_f32_e32 v107, v107, v252
	v_max_f32_e32 v19, v19, v20
	v_max_f32_e32 v39, v39, v116
	v_max_f32_e32 v0, v0, v43
	v_max_f32_e32 v41, v41, v53
	v_max_f32_e32 v255, v255, v42
	v_max_f32_e32 v24, v24, v54
	v_max_f32_e32 v38, v38, v40
	v_max_f32_e32 v26, v26, v149
	v_max_f32_e32 v37, v37, v57
	v_max_f32_e32 v27, v27, v16
	v_max_f32_e32 v109, v109, v55
	v_max_f32_e32 v4, v4, v35
	v_max_f32_e32 v101, v101, v113
	v_max_f32_e32 v47, v47, v253
	v_max_f32_e32 v34, v150, v38
	v_min_f32_e32 v38, v150, v38
	v_max_f32_e32 v114, v107, v26
	v_min_f32_e32 v26, v107, v26
	v_max_f32_e32 v32, v19, v37
	v_min_f32_e32 v37, v19, v37
	v_max_f32_e32 v33, v39, v27
	v_min_f32_e32 v27, v39, v27
	v_max_f32_e32 v117, v0, v109
	v_min_f32_e32 v109, v0, v109
	v_max_f32_e32 v1, v41, v4
	v_min_f32_e32 v4, v41, v4
	v_max_f32_e32 v36, v255, v101
	v_min_f32_e32 v101, v255, v101
	v_max_f32_e32 v121, v24, v47
	v_min_f32_e32 v47, v24, v47
	v_max_f32_e32 v50, v34, v117
	v_min_f32_e32 v117, v34, v117
	v_max_f32_e32 v122, v114, v1
	v_min_f32_e32 v1, v114, v1
	v_max_f32_e32 v52, v32, v36
	v_min_f32_e32 v36, v32, v36
	v_max_f32_e32 v48, v33, v121
	v_min_f32_e32 v121, v33, v121
	v_max_f32_e32 v49, v38, v109
	v_min_f32_e32 v109, v38, v109
	v_max_f32_e32 v51, v26, v4
	v_min_f32_e32 v4, v26, v4
	v_max_f32_e32 v127, v37, v101
	v_min_f32_e32 v101, v37, v101
	v_max_f32_e32 v151, v27, v47
	v_min_f32_e32 v47, v27, v47
	v_max_f32_e32 v102, v50, v52
	v_min_f32_e32 v52, v50, v52
	v_max_f32_e32 v3, v122, v48
	v_min_f32_e32 v48, v122, v48
	v_max_f32_e32 v23, v117, v36
	v_min_f32_e32 v36, v117, v36
	v_max_f32_e32 v124, v1, v121
	v_min_f32_e32 v121, v1, v121
	v_max_f32_e32 v25, v49, v127
	v_min_f32_e32 v127, v49, v127
	v_max_f32_e32 v249, v51, v151
	v_min_f32_e32 v151, v51, v151
	v_max_f32_e32 v8, v109, v101
	v_min_f32_e32 v101, v109, v101
	v_max_f32_e32 v22, v4, v47
	v_min_f32_e32 v47, v4, v47
	v_max_f32_e32 v10, v102, v3
	v_min_f32_e32 v3, v102, v3
	v_max_f32_e32 v21, v52, v48
	v_min_f32_e32 v48, v52, v48
	v_max_f32_e32 v11, v23, v124
	v_min_f32_e32 v124, v23, v124
	v_max_f32_e32 v118, v36, v121
	v_min_f32_e32 v121, v36, v121
	v_max_f32_e32 v123, v25, v249
	v_min_f32_e32 v249, v25, v249
	v_max_f32_e32 v110, v127, v151
	v_min_f32_e32 v151, v127, v151
	v_max_f32_e32 v31, v8, v22
	v_min_f32_e32 v22, v8, v22
	v_max_f32_e32 v105, v101, v47
	v_min_f32_e32 v47, v101, v47
	v_max_f32_e32 v250, v250, v47
	v_max_f32_e32 v103, v103, v105
	v_max_f32_e32 v106, v106, v22
	v_max_f32_e32 v13, v13, v31
	v_max_f32_e32 v18, v18, v151
	v_max_f32_e32 v100, v100, v110
	v_max_f32_e32 v98, v98, v249
	v_max_f32_e32 v12, v12, v123
	v_max_f32_e32 v17, v17, v121
	v_max_f32_e32 v2, v2, v118
	v_max_f32_e32 v254, v254, v124
	v_max_f32_e32 v96, v96, v11
	v_max_f32_e32 v125, v125, v48
	v_max_f32_e32 v97, v97, v21
	v_max_f32_e32 v112, v112, v3
	v_max_f32_e32 v15, v15, v10
	v_max_f32_e32 v120, v250, v17
	v_min_f32_e32 v17, v250, v17
	v_max_f32_e32 v126, v103, v2
	v_min_f32_e32 v2, v103, v2
	v_max_f32_e32 v7, v106, v254
	v_min_f32_e32 v254, v106, v254
	v_max_f32_e32 v115, v13, v96
	v_min_f32_e32 v96, v13, v96
	v_max_f32_e32 v9, v18, v125
	v_min_f32_e32 v125, v18, v125
	v_max_f32_e32 v147, v100, v97
	v_min_f32_e32 v97, v100, v97
	v_max_f32_e32 v144, v98, v112
	v_min_f32_e32 v112, v98, v112
	v_max_f32_e32 v56, v12, v15
	v_min_f32_e32 v15, v12, v15
	v_max_f32_e32 v58, v120, v9
	v_min_f32_e32 v9, v120, v9
	v_max_f32_e32 v59, v126, v147
	v_min_f32_e32 v147, v126, v147
	v_max_f32_e32 v148, v7, v144
	v_min_f32_e32 v144, v7, v144
	v_max_f32_e32 v6, v115, v56
	v_min_f32_e32 v56, v115, v56
	v_max_f32_e32 v145, v17, v125
	v_min_f32_e32 v125, v17, v125
	v_max_f32_e32 v5, v2, v97
	v_min_f32_e32 v97, v2, v97
	v_max_f32_e32 v146, v254, v112
	v_min_f32_e32 v112, v254, v112
	v_max_f32_e32 v251, v96, v15
	v_min_f32_e32 v15, v96, v15
	v_max_f32_e32 v60, v58, v148
	v_min_f32_e32 v148, v58, v148
	v_max_f32_e32 v46, v59, v6
	v_min_f32_e32 v6, v59, v6
	v_max_f32_e32 v30, v9, v144
	v_min_f32_e32 v144, v9, v144
	v_max_f32_e32 v44, v147, v56
	v_min_f32_e32 v56, v147, v56
	v_max_f32_e32 v45, v145, v146
	v_min_f32_e32 v146, v145, v146
	v_max_f32_e32 v111, v5, v251
	v_min_f32_e32 v251, v5, v251
	v_max_f32_e32 v119, v125, v112
	v_min_f32_e32 v112, v125, v112
	v_max_f32_e32 v29, v97, v15
	v_min_f32_e32 v15, v97, v15
	v_max_f32_e32 v62, v60, v46
	v_min_f32_e32 v46, v60, v46
	v_max_f32_e32 v61, v148, v6
	v_min_f32_e32 v6, v148, v6
	v_max_f32_e32 v28, v30, v44
	v_min_f32_e32 v44, v30, v44
	v_max_f32_e32 v99, v144, v56
	v_min_f32_e32 v56, v144, v56
	v_max_f32_e32 v14, v45, v111
	v_min_f32_e32 v111, v45, v111
	v_max_f32_e32 v108, v146, v251
	v_min_f32_e32 v251, v146, v251
	v_max_f32_e32 v104, v119, v29
	v_min_f32_e32 v29, v119, v29
	v_max_f32_e32 v253, v112, v15
	v_min_f32_e32 v15, v112, v15
	v_mov_b32_e32 v113, v62
	v_mov_b32_e32 v35, v46
	v_mov_b32_e32 v55, v61
	v_mov_b32_e32 v16, v6
	v_mov_b32_e32 v57, v28
	v_mov_b32_e32 v149, v44
	v_mov_b32_e32 v40, v99
	v_mov_b32_e32 v54, v56
	v_mov_b32_e32 v42, v14
	v_mov_b32_e32 v53, v111
	v_mov_b32_e32 v43, v108
	v_mov_b32_e32 v116, v251
	v_mov_b32_e32 v20, v104
	v_mov_b32_e32 v252, v29
	v_mov_b32_e32 v63, v253
	v_mov_b32_e32 v150, v15
	s_nop 1
	v_permlane32_swap_b32_e32 v62, v113
	v_permlane32_swap_b32_e32 v46, v35
	v_permlane32_swap_b32_e32 v61, v55
	v_permlane32_swap_b32_e32 v6, v16
	v_permlane32_swap_b32_e32 v28, v57
	v_permlane32_swap_b32_e32 v44, v149
	v_permlane32_swap_b32_e32 v99, v40
	v_permlane32_swap_b32_e32 v56, v54
	v_permlane32_swap_b32_e32 v14, v42
	v_permlane32_swap_b32_e32 v111, v53
	v_permlane32_swap_b32_e32 v108, v43
	v_permlane32_swap_b32_e32 v251, v116
	v_permlane32_swap_b32_e32 v104, v20
	v_permlane32_swap_b32_e32 v29, v252
	v_permlane32_swap_b32_e32 v253, v63
	v_permlane32_swap_b32_e32 v15, v150
	s_nop 1
	v_max_f32_e32 v62, v62, v150
	v_max_f32_e32 v46, v46, v63
	v_max_f32_e32 v61, v61, v252
	v_max_f32_e32 v6, v6, v20
	v_max_f32_e32 v28, v28, v116
	v_max_f32_e32 v44, v44, v43
	v_max_f32_e32 v99, v99, v53
	v_max_f32_e32 v56, v56, v42
	v_max_f32_e32 v14, v14, v54
	v_max_f32_e32 v111, v111, v40
	v_max_f32_e32 v108, v108, v149
	v_max_f32_e32 v251, v251, v57
	v_max_f32_e32 v104, v104, v16
	v_max_f32_e32 v29, v29, v55
	v_max_f32_e32 v253, v253, v35
	v_max_f32_e32 v15, v15, v113
	v_max_f32_e32 v107, v62, v14
	v_min_f32_e32 v14, v62, v14
	v_max_f32_e32 v19, v46, v111
	v_min_f32_e32 v111, v46, v111
	v_max_f32_e32 v39, v61, v108
	v_min_f32_e32 v108, v61, v108
	v_max_f32_e32 v0, v6, v251
	v_min_f32_e32 v251, v6, v251
	v_max_f32_e32 v41, v28, v104
	v_min_f32_e32 v104, v28, v104
	v_max_f32_e32 v255, v44, v29
	v_min_f32_e32 v29, v44, v29
	v_max_f32_e32 v24, v99, v253
	v_min_f32_e32 v253, v99, v253
	v_max_f32_e32 v34, v56, v15
	v_min_f32_e32 v15, v56, v15
	v_max_f32_e32 v114, v107, v41
	v_min_f32_e32 v41, v107, v41
	v_max_f32_e32 v32, v19, v255
	v_min_f32_e32 v255, v19, v255
	v_max_f32_e32 v33, v39, v24
	v_min_f32_e32 v24, v39, v24
	v_max_f32_e32 v38, v0, v34
	v_min_f32_e32 v34, v0, v34
	v_max_f32_e32 v26, v14, v104
	v_min_f32_e32 v104, v14, v104
	v_max_f32_e32 v37, v111, v29
	v_min_f32_e32 v29, v111, v29
	v_max_f32_e32 v27, v108, v253
	v_min_f32_e32 v253, v108, v253
	v_max_f32_e32 v50, v251, v15
	v_min_f32_e32 v15, v251, v15
	v_max_f32_e32 v122, v114, v33
	v_min_f32_e32 v33, v114, v33
	v_max_f32_e32 v117, v32, v38
	v_min_f32_e32 v38, v32, v38
	v_max_f32_e32 v1, v41, v24
	v_min_f32_e32 v24, v41, v24
	v_max_f32_e32 v49, v255, v34
	v_min_f32_e32 v34, v255, v34
	v_max_f32_e32 v51, v26, v27
	v_min_f32_e32 v27, v26, v27
	v_max_f32_e32 v109, v37, v50
	v_min_f32_e32 v50, v37, v50
	v_max_f32_e32 v4, v104, v253
	v_min_f32_e32 v253, v104, v253
	v_max_f32_e32 v102, v29, v15
	v_min_f32_e32 v15, v29, v15
	v_max_f32_e32 v128, v122, v117
	v_min_f32_e32 v129, v122, v117
	v_max_f32_e32 v130, v33, v38
	v_min_f32_e32 v131, v33, v38
	v_max_f32_e32 v132, v1, v49
	v_min_f32_e32 v133, v1, v49
	v_max_f32_e32 v134, v24, v34
	v_min_f32_e32 v135, v24, v34
	v_max_f32_e32 v136, v51, v109
	v_min_f32_e32 v137, v51, v109
	v_max_f32_e32 v138, v27, v50
	v_min_f32_e32 v139, v27, v50
	v_max_f32_e32 v140, v4, v102
	v_min_f32_e32 v141, v4, v102
	v_max_f32_e32 v142, v253, v15
	v_min_f32_e32 v143, v253, v15
	ds_write_b8 v240, v128 offset:0
	ds_write_b8 v240, v129 offset:1
	ds_write_b8 v240, v130 offset:2
	ds_write_b8 v240, v131 offset:3
	ds_write_b8 v240, v132 offset:4
	ds_write_b8 v240, v133 offset:5
	ds_write_b8 v240, v134 offset:6
	ds_write_b8 v240, v135 offset:7
	ds_write_b8 v240, v136 offset:8
	ds_write_b8 v240, v137 offset:9
	ds_write_b8 v240, v138 offset:10
	ds_write_b8 v240, v139 offset:11
	ds_write_b8 v240, v140 offset:12
	ds_write_b8 v240, v141 offset:13
	ds_write_b8 v240, v142 offset:14
	ds_write_b8 v240, v143 offset:15
	ds_read_b128 v[96:99], v231 offset:32768
	ds_read_b128 v[100:103], v232 offset:32768
	ds_read_b128 v[104:107], v233 offset:32768
	ds_read_b128 v[108:111], v234 offset:32768
	ds_read_b128 v[112:115], v235 offset:32768
	ds_read_b128 v[116:119], v236 offset:32768
	ds_read_b128 v[120:123], v237 offset:32768
	ds_read_b128 v[124:127], v238 offset:32768
	s_waitcnt vmcnt(0)
	s_waitcnt lgkmcnt(4)
	v_mfma_f32_32x32x16_bf16 v[0:15], v[96:99], v[64:67], 0
	v_mfma_f32_32x32x16_bf16 v[0:15], v[100:103], v[68:71], v[0:15]
	v_mfma_f32_32x32x16_bf16 v[0:15], v[104:107], v[72:75], v[0:15]
	v_mfma_f32_32x32x16_bf16 v[0:15], v[108:111], v[76:79], v[0:15]
	ds_read_b128 v[96:99], v231 offset:40960
	ds_read_b128 v[100:103], v232 offset:40960
	ds_read_b128 v[104:107], v233 offset:40960
	ds_read_b128 v[108:111], v234 offset:40960
	s_waitcnt lgkmcnt(4)
	v_mfma_f32_32x32x16_bf16 v[0:15], v[112:115], v[80:83], v[0:15]
	v_mfma_f32_32x32x16_bf16 v[0:15], v[116:119], v[84:87], v[0:15]
	v_mfma_f32_32x32x16_bf16 v[0:15], v[120:123], v[88:91], v[0:15]
	v_mfma_f32_32x32x16_bf16 v[0:15], v[124:127], v[92:95], v[0:15]
	ds_read_b128 v[112:115], v235 offset:40960
	ds_read_b128 v[116:119], v236 offset:40960
	ds_read_b128 v[120:123], v237 offset:40960
	ds_read_b128 v[124:127], v238 offset:40960
	s_waitcnt lgkmcnt(4)
	v_mfma_f32_32x32x16_bf16 v[16:31], v[96:99], v[64:67], 0
	v_mfma_f32_32x32x16_bf16 v[16:31], v[100:103], v[68:71], v[16:31]
	v_mfma_f32_32x32x16_bf16 v[16:31], v[104:107], v[72:75], v[16:31]
	v_mfma_f32_32x32x16_bf16 v[16:31], v[108:111], v[76:79], v[16:31]
	ds_read_b128 v[96:99], v231 offset:49152
	ds_read_b128 v[100:103], v232 offset:49152
	ds_read_b128 v[104:107], v233 offset:49152
	ds_read_b128 v[108:111], v234 offset:49152
	s_waitcnt lgkmcnt(4)
	v_mfma_f32_32x32x16_bf16 v[16:31], v[112:115], v[80:83], v[16:31]
	v_mfma_f32_32x32x16_bf16 v[16:31], v[116:119], v[84:87], v[16:31]
	v_mfma_f32_32x32x16_bf16 v[16:31], v[120:123], v[88:91], v[16:31]
	v_mfma_f32_32x32x16_bf16 v[16:31], v[124:127], v[92:95], v[16:31]
	ds_read_b128 v[112:115], v235 offset:49152
	ds_read_b128 v[116:119], v236 offset:49152
	ds_read_b128 v[120:123], v237 offset:49152
	ds_read_b128 v[124:127], v238 offset:49152
	s_waitcnt lgkmcnt(4)
	v_mfma_f32_32x32x16_bf16 v[32:47], v[96:99], v[64:67], 0
	v_mfma_f32_32x32x16_bf16 v[32:47], v[100:103], v[68:71], v[32:47]
	v_mfma_f32_32x32x16_bf16 v[32:47], v[104:107], v[72:75], v[32:47]
	v_mfma_f32_32x32x16_bf16 v[32:47], v[108:111], v[76:79], v[32:47]
	ds_read_b128 v[96:99], v231 offset:57344
	ds_read_b128 v[100:103], v232 offset:57344
	ds_read_b128 v[104:107], v233 offset:57344
	ds_read_b128 v[108:111], v234 offset:57344
	s_waitcnt lgkmcnt(4)
	v_mfma_f32_32x32x16_bf16 v[32:47], v[112:115], v[80:83], v[32:47]
	v_mfma_f32_32x32x16_bf16 v[32:47], v[116:119], v[84:87], v[32:47]
	v_mfma_f32_32x32x16_bf16 v[32:47], v[120:123], v[88:91], v[32:47]
	v_mfma_f32_32x32x16_bf16 v[32:47], v[124:127], v[92:95], v[32:47]
	ds_read_b128 v[112:115], v235 offset:57344
	ds_read_b128 v[116:119], v236 offset:57344
	ds_read_b128 v[120:123], v237 offset:57344
	ds_read_b128 v[124:127], v238 offset:57344
	s_waitcnt lgkmcnt(4)
	v_mfma_f32_32x32x16_bf16 v[48:63], v[96:99], v[64:67], 0
	v_mfma_f32_32x32x16_bf16 v[48:63], v[100:103], v[68:71], v[48:63]
	v_mfma_f32_32x32x16_bf16 v[48:63], v[104:107], v[72:75], v[48:63]
	v_mfma_f32_32x32x16_bf16 v[48:63], v[108:111], v[76:79], v[48:63]
	s_waitcnt lgkmcnt(0)
	v_mfma_f32_32x32x16_bf16 v[48:63], v[112:115], v[80:83], v[48:63]
	v_mfma_f32_32x32x16_bf16 v[48:63], v[116:119], v[84:87], v[48:63]
	v_mfma_f32_32x32x16_bf16 v[48:63], v[120:123], v[88:91], v[48:63]
	v_mfma_f32_32x32x16_bf16 v[48:63], v[124:127], v[92:95], v[48:63]
	s_nop 11
	v_and_or_b32 v0, v0, s6, v160
	v_and_or_b32 v1, v1, s6, v161
	v_and_or_b32 v2, v2, s6, v162
	v_and_or_b32 v3, v3, s6, v163
	v_and_or_b32 v4, v4, s6, v164
	v_and_or_b32 v5, v5, s6, v165
	v_and_or_b32 v6, v6, s6, v166
	v_and_or_b32 v7, v7, s6, v167
	v_and_or_b32 v8, v8, s6, v168
	v_and_or_b32 v9, v9, s6, v169
	v_and_or_b32 v10, v10, s6, v170
	v_and_or_b32 v11, v11, s6, v171
	v_and_or_b32 v12, v12, s6, v172
	v_and_or_b32 v13, v13, s6, v173
	v_and_or_b32 v14, v14, s6, v174
	v_and_or_b32 v15, v15, s6, v175
	v_and_or_b32 v16, v16, s6, v176
	v_and_or_b32 v17, v17, s6, v177
	v_and_or_b32 v18, v18, s6, v178
	v_and_or_b32 v19, v19, s6, v179
	v_and_or_b32 v20, v20, s6, v180
	v_and_or_b32 v21, v21, s6, v181
	v_and_or_b32 v22, v22, s6, v182
	v_and_or_b32 v23, v23, s6, v183
	v_and_or_b32 v24, v24, s6, v184
	v_and_or_b32 v25, v25, s6, v185
	v_and_or_b32 v26, v26, s6, v186
	v_and_or_b32 v27, v27, s6, v187
	v_and_or_b32 v28, v28, s6, v188
	v_and_or_b32 v29, v29, s6, v189
	v_and_or_b32 v30, v30, s6, v190
	v_and_or_b32 v31, v31, s6, v191
	v_and_or_b32 v32, v32, s6, v192
	v_and_or_b32 v33, v33, s6, v193
	v_and_or_b32 v34, v34, s6, v194
	v_and_or_b32 v35, v35, s6, v195
	v_and_or_b32 v36, v36, s6, v196
	v_and_or_b32 v37, v37, s6, v204
	v_and_or_b32 v38, v38, s6, v205
	v_and_or_b32 v39, v39, s6, v206
	v_and_or_b32 v40, v40, s6, v207
	v_and_or_b32 v41, v41, s6, v208
	v_and_or_b32 v42, v42, s6, v209
	v_and_or_b32 v43, v43, s6, v210
	v_and_or_b32 v44, v44, s6, v211
	v_and_or_b32 v45, v45, s6, v212
	v_and_or_b32 v46, v46, s6, v213
	v_and_or_b32 v47, v47, s6, v214
	v_and_or_b32 v48, v48, s6, v215
	v_and_or_b32 v49, v49, s6, v216
	v_and_or_b32 v50, v50, s6, v217
	v_and_or_b32 v51, v51, s6, v218
	v_and_or_b32 v52, v52, s6, v219
	v_and_or_b32 v53, v53, s6, v220
	v_and_or_b32 v54, v54, s6, v221
	v_and_or_b32 v55, v55, s6, v222
	v_and_or_b32 v56, v56, s6, v223
	v_and_or_b32 v57, v57, s6, v224
	v_and_or_b32 v58, v58, s6, v225
	v_and_or_b32 v59, v59, s6, v226
	v_and_or_b32 v60, v60, s6, v227
	v_and_or_b32 v61, v61, s6, v228
	v_and_or_b32 v62, v62, s6, v229
	v_and_or_b32 v63, v63, s6, v230
	v_max_f32_e32 v144, v0, v13
	v_min_f32_e32 v13, v0, v13
	v_max_f32_e32 v145, v1, v12
	v_min_f32_e32 v12, v1, v12
	v_max_f32_e32 v146, v2, v15
	v_min_f32_e32 v15, v2, v15
	v_max_f32_e32 v147, v3, v14
	v_min_f32_e32 v14, v3, v14
	v_max_f32_e32 v148, v4, v8
	v_min_f32_e32 v8, v4, v8
	v_max_f32_e32 v149, v5, v6
	v_min_f32_e32 v6, v5, v6
	v_max_f32_e32 v150, v7, v11
	v_min_f32_e32 v11, v7, v11
	v_max_f32_e32 v151, v9, v10
	v_min_f32_e32 v10, v9, v10
	v_max_f32_e32 v249, v144, v149
	v_min_f32_e32 v149, v144, v149
	v_max_f32_e32 v250, v145, v150
	v_min_f32_e32 v150, v145, v150
	v_max_f32_e32 v251, v146, v151
	v_min_f32_e32 v151, v146, v151
	v_max_f32_e32 v252, v147, v148
	v_min_f32_e32 v148, v147, v148
	v_max_f32_e32 v253, v6, v13
	v_min_f32_e32 v13, v6, v13
	v_max_f32_e32 v254, v8, v14
	v_min_f32_e32 v14, v8, v14
	v_max_f32_e32 v255, v10, v15
	v_min_f32_e32 v15, v10, v15
	v_max_f32_e32 v96, v11, v12
	v_min_f32_e32 v12, v11, v12
	v_max_f32_e32 v97, v249, v250
	v_min_f32_e32 v250, v249, v250
	v_max_f32_e32 v98, v251, v252
	v_min_f32_e32 v252, v251, v252
	v_max_f32_e32 v99, v148, v149
	v_min_f32_e32 v149, v148, v149
	v_max_f32_e32 v100, v253, v254
	v_min_f32_e32 v254, v253, v254
	v_max_f32_e32 v101, v150, v151
	v_min_f32_e32 v151, v150, v151
	v_max_f32_e32 v102, v255, v96
	v_min_f32_e32 v96, v255, v96
	v_max_f32_e32 v103, v12, v13
	v_min_f32_e32 v13, v12, v13
	v_max_f32_e32 v104, v14, v15
	v_min_f32_e32 v15, v14, v15
	v_max_f32_e32 v105, v97, v98
	v_min_f32_e32 v98, v97, v98
	v_max_f32_e32 v106, v250, v252
	v_min_f32_e32 v252, v250, v252
	v_max_f32_e32 v107, v99, v102
	v_min_f32_e32 v102, v99, v102
	v_max_f32_e32 v108, v149, v96
	v_min_f32_e32 v96, v149, v96
	v_max_f32_e32 v109, v100, v101
	v_min_f32_e32 v101, v100, v101
	v_max_f32_e32 v110, v254, v151
	v_min_f32_e32 v151, v254, v151
	v_max_f32_e32 v111, v103, v104
	v_min_f32_e32 v104, v103, v104
	v_max_f32_e32 v112, v13, v15
	v_min_f32_e32 v15, v13, v15
	v_max_f32_e32 v113, v106, v98
	v_min_f32_e32 v98, v106, v98
	v_max_f32_e32 v114, v252, v111
	v_min_f32_e32 v111, v252, v111
	v_max_f32_e32 v115, v107, v109
	v_min_f32_e32 v109, v107, v109
	v_max_f32_e32 v116, v108, v101
	v_min_f32_e32 v101, v108, v101
	v_max_f32_e32 v117, v110, v102
	v_min_f32_e32 v102, v110, v102
	v_max_f32_e32 v118, v151, v96
	v_min_f32_e32 v96, v151, v96
	v_max_f32_e32 v119, v112, v104
	v_min_f32_e32 v104, v112, v104
	v_max_f32_e32 v120, v113, v115
	v_min_f32_e32 v115, v113, v115
	v_max_f32_e32 v121, v98, v109
	v_min_f32_e32 v109, v98, v109
	v_max_f32_e32 v122, v116, v117
	v_min_f32_e32 v117, v116, v117
	v_max_f32_e32 v123, v101, v102
	v_min_f32_e32 v102, v101, v102
	v_max_f32_e32 v124, v118, v119
	v_min_f32_e32 v119, v118, v119
	v_max_f32_e32 v125, v96, v104
	v_min_f32_e32 v104, v96, v104
	v_max_f32_e32 v126, v121, v115
	v_min_f32_e32 v115, v121, v115
	v_max_f32_e32 v127, v114, v109
	v_min_f32_e32 v109, v114, v109
	v_max_f32_e32 v64, v124, v111
	v_min_f32_e32 v111, v124, v111
	v_max_f32_e32 v65, v125, v119
	v_min_f32_e32 v119, v125, v119
	v_max_f32_e32 v66, v127, v122
	v_min_f32_e32 v122, v127, v122
	v_max_f32_e32 v67, v109, v117
	v_min_f32_e32 v117, v109, v117
	v_max_f32_e32 v68, v123, v64
	v_min_f32_e32 v64, v123, v64
	v_max_f32_e32 v69, v102, v111
	v_min_f32_e32 v111, v102, v111
	v_max_f32_e32 v70, v66, v115
	v_min_f32_e32 v115, v66, v115
	v_max_f32_e32 v71, v122, v67
	v_min_f32_e32 v67, v122, v67
	v_max_f32_e32 v72, v68, v117
	v_min_f32_e32 v117, v68, v117
	v_max_f32_e32 v73, v64, v69
	v_min_f32_e32 v69, v64, v69
	v_max_f32_e32 v74, v65, v111
	v_min_f32_e32 v111, v65, v111
	v_max_f32_e32 v75, v67, v72
	v_min_f32_e32 v72, v67, v72
	v_max_f32_e32 v76, v117, v73
	v_min_f32_e32 v73, v117, v73
	v_max_f32_e32 v77, v16, v29
	v_min_f32_e32 v29, v16, v29
	v_max_f32_e32 v78, v17, v28
	v_min_f32_e32 v28, v17, v28
	v_max_f32_e32 v79, v18, v31
	v_min_f32_e32 v31, v18, v31
	v_max_f32_e32 v80, v19, v30
	v_min_f32_e32 v30, v19, v30
	v_max_f32_e32 v81, v20, v24
	v_min_f32_e32 v24, v20, v24
	v_max_f32_e32 v82, v21, v22
	v_min_f32_e32 v22, v21, v22
	v_max_f32_e32 v83, v23, v27
	v_min_f32_e32 v27, v23, v27
	v_max_f32_e32 v84, v25, v26
	v_min_f32_e32 v26, v25, v26
	v_max_f32_e32 v85, v77, v82
	v_min_f32_e32 v82, v77, v82
	v_max_f32_e32 v86, v78, v83
	v_min_f32_e32 v83, v78, v83
	v_max_f32_e32 v87, v79, v84
	v_min_f32_e32 v84, v79, v84
	v_max_f32_e32 v88, v80, v81
	v_min_f32_e32 v81, v80, v81
	v_max_f32_e32 v89, v22, v29
	v_min_f32_e32 v29, v22, v29
	v_max_f32_e32 v90, v24, v30
	v_min_f32_e32 v30, v24, v30
	v_max_f32_e32 v91, v26, v31
	v_min_f32_e32 v31, v26, v31
	v_max_f32_e32 v92, v27, v28
	v_min_f32_e32 v28, v27, v28
	v_max_f32_e32 v93, v85, v86
	v_min_f32_e32 v86, v85, v86
	v_max_f32_e32 v94, v87, v88
	v_min_f32_e32 v88, v87, v88
	v_max_f32_e32 v95, v81, v82
	v_min_f32_e32 v82, v81, v82
	v_max_f32_e32 v0, v89, v90
	v_min_f32_e32 v90, v89, v90
	v_max_f32_e32 v1, v83, v84
	v_min_f32_e32 v84, v83, v84
	v_max_f32_e32 v2, v91, v92
	v_min_f32_e32 v92, v91, v92
	v_max_f32_e32 v3, v28, v29
	v_min_f32_e32 v29, v28, v29
	v_max_f32_e32 v4, v30, v31
	v_min_f32_e32 v31, v30, v31
	v_max_f32_e32 v5, v93, v94
	v_min_f32_e32 v94, v93, v94
	v_max_f32_e32 v7, v86, v88
	v_min_f32_e32 v88, v86, v88
	v_max_f32_e32 v9, v95, v2
	v_min_f32_e32 v2, v95, v2
	v_max_f32_e32 v144, v82, v92
	v_min_f32_e32 v92, v82, v92
	v_max_f32_e32 v145, v0, v1
	v_min_f32_e32 v1, v0, v1
	v_max_f32_e32 v146, v90, v84
	v_min_f32_e32 v84, v90, v84
	v_max_f32_e32 v147, v3, v4
	v_min_f32_e32 v4, v3, v4
	v_max_f32_e32 v6, v29, v31
	v_min_f32_e32 v31, v29, v31
	v_max_f32_e32 v8, v7, v94
	v_min_f32_e32 v94, v7, v94
	v_max_f32_e32 v10, v88, v147
	v_min_f32_e32 v147, v88, v147
	v_max_f32_e32 v11, v9, v145
	v_min_f32_e32 v145, v9, v145
	v_max_f32_e32 v249, v144, v1
	v_min_f32_e32 v1, v144, v1
	v_max_f32_e32 v251, v146, v2
	v_min_f32_e32 v2, v146, v2
	v_max_f32_e32 v148, v84, v92
	v_min_f32_e32 v92, v84, v92
	v_max_f32_e32 v253, v6, v4
	v_min_f32_e32 v4, v6, v4
	v_max_f32_e32 v150, v8, v11
	v_min_f32_e32 v11, v8, v11
	v_max_f32_e32 v255, v94, v145
	v_min_f32_e32 v145, v94, v145
	v_max_f32_e32 v12, v249, v251
	v_min_f32_e32 v251, v249, v251
	v_max_f32_e32 v14, v1, v2
	v_min_f32_e32 v2, v1, v2
	v_max_f32_e32 v97, v148, v253
	v_min_f32_e32 v253, v148, v253
	v_max_f32_e32 v250, v92, v4
	v_min_f32_e32 v4, v92, v4
	v_max_f32_e32 v99, v255, v11
	v_min_f32_e32 v11, v255, v11
	v_max_f32_e32 v149, v10, v145
	v_min_f32_e32 v145, v10, v145
	v_max_f32_e32 v100, v97, v147
	v_min_f32_e32 v147, v97, v147
	v_max_f32_e32 v254, v250, v253
	v_min_f32_e32 v253, v250, v253
	v_max_f32_e32 v103, v149, v12
	v_min_f32_e32 v12, v149, v12
	v_max_f32_e32 v13, v145, v251
	v_min_f32_e32 v251, v145, v251
	v_max_f32_e32 v106, v14, v100
	v_min_f32_e32 v100, v14, v100
	v_max_f32_e32 v252, v2, v147
	v_min_f32_e32 v147, v2, v147
	v_max_f32_e32 v107, v103, v11
	v_min_f32_e32 v11, v103, v11
	v_max_f32_e32 v108, v12, v13
	v_min_f32_e32 v13, v12, v13
	v_max_f32_e32 v110, v106, v251
	v_min_f32_e32 v251, v106, v251
	v_max_f32_e32 v151, v100, v252
	v_min_f32_e32 v252, v100, v252
	v_max_f32_e32 v112, v254, v147
	v_min_f32_e32 v147, v254, v147
	v_max_f32_e32 v113, v13, v110
	v_min_f32_e32 v110, v13, v110
	v_max_f32_e32 v98, v251, v151
	v_min_f32_e32 v151, v251, v151
	v_max_f32_e32 v116, v32, v45
	v_min_f32_e32 v45, v32, v45
	v_max_f32_e32 v101, v33, v44
	v_min_f32_e32 v44, v33, v44
	v_max_f32_e32 v118, v34, v47
	v_min_f32_e32 v47, v34, v47
	v_max_f32_e32 v96, v35, v46
	v_min_f32_e32 v46, v35, v46
	v_max_f32_e32 v121, v36, v40
	v_min_f32_e32 v40, v36, v40
	v_max_f32_e32 v114, v37, v38
	v_min_f32_e32 v38, v37, v38
	v_max_f32_e32 v124, v39, v43
	v_min_f32_e32 v43, v39, v43
	v_max_f32_e32 v125, v41, v42
	v_min_f32_e32 v42, v41, v42
	v_max_f32_e32 v127, v116, v114
	v_min_f32_e32 v114, v116, v114
	v_max_f32_e32 v109, v101, v124
	v_min_f32_e32 v124, v101, v124
	v_max_f32_e32 v123, v118, v125
	v_min_f32_e32 v125, v118, v125
	v_max_f32_e32 v102, v96, v121
	v_min_f32_e32 v121, v96, v121
	v_max_f32_e32 v66, v38, v45
	v_min_f32_e32 v45, v38, v45
	v_max_f32_e32 v122, v40, v46
	v_min_f32_e32 v46, v40, v46
	v_max_f32_e32 v68, v42, v47
	v_min_f32_e32 v47, v42, v47
	v_max_f32_e32 v64, v43, v44
	v_min_f32_e32 v44, v43, v44
	v_max_f32_e32 v65, v127, v109
	v_min_f32_e32 v109, v127, v109
	v_max_f32_e32 v67, v123, v102
	v_min_f32_e32 v102, v123, v102
	v_max_f32_e32 v117, v121, v114
	v_min_f32_e32 v114, v121, v114
	v_max_f32_e32 v16, v66, v122
	v_min_f32_e32 v122, v66, v122
	v_max_f32_e32 v17, v124, v125
	v_min_f32_e32 v125, v124, v125
	v_max_f32_e32 v18, v68, v64
	v_min_f32_e32 v64, v68, v64
	v_max_f32_e32 v19, v44, v45
	v_min_f32_e32 v45, v44, v45
	v_max_f32_e32 v20, v46, v47
	v_min_f32_e32 v47, v46, v47
	v_max_f32_e32 v21, v65, v67
	v_min_f32_e32 v67, v65, v67
	v_max_f32_e32 v23, v109, v102
	v_min_f32_e32 v102, v109, v102
	v_max_f32_e32 v25, v117, v18
	v_min_f32_e32 v18, v117, v18
	v_max_f32_e32 v77, v114, v64
	v_min_f32_e32 v64, v114, v64
	v_max_f32_e32 v78, v16, v17
	v_min_f32_e32 v17, v16, v17
	v_max_f32_e32 v79, v122, v125
	v_min_f32_e32 v125, v122, v125
	v_max_f32_e32 v80, v19, v20
	v_min_f32_e32 v20, v19, v20
	v_max_f32_e32 v22, v45, v47
	v_min_f32_e32 v47, v45, v47
	v_max_f32_e32 v24, v23, v67
	v_min_f32_e32 v67, v23, v67
	v_max_f32_e32 v26, v102, v80
	v_min_f32_e32 v80, v102, v80
	v_max_f32_e32 v27, v25, v78
	v_min_f32_e32 v78, v25, v78
	v_max_f32_e32 v85, v77, v17
	v_min_f32_e32 v17, v77, v17
	v_max_f32_e32 v87, v79, v18
	v_min_f32_e32 v18, v79, v18
	v_max_f32_e32 v81, v125, v64
	v_min_f32_e32 v64, v125, v64
	v_max_f32_e32 v89, v22, v20
	v_min_f32_e32 v20, v22, v20
	v_max_f32_e32 v83, v24, v27
	v_min_f32_e32 v27, v24, v27
	v_max_f32_e32 v91, v67, v78
	v_min_f32_e32 v78, v67, v78
	v_max_f32_e32 v28, v85, v87
	v_min_f32_e32 v87, v85, v87
	v_max_f32_e32 v30, v17, v18
	v_min_f32_e32 v18, v17, v18
	v_max_f32_e32 v93, v81, v89
	v_min_f32_e32 v89, v81, v89
	v_max_f32_e32 v86, v64, v20
	v_min_f32_e32 v20, v64, v20
	v_max_f32_e32 v95, v91, v27
	v_min_f32_e32 v27, v91, v27
	v_max_f32_e32 v82, v26, v78
	v_min_f32_e32 v78, v26, v78
	v_max_f32_e32 v0, v93, v80
	v_min_f32_e32 v80, v93, v80
	v_max_f32_e32 v90, v86, v89
	v_min_f32_e32 v89, v86, v89
	v_max_f32_e32 v3, v82, v28
	v_min_f32_e32 v28, v82, v28
	v_max_f32_e32 v29, v78, v87
	v_min_f32_e32 v87, v78, v87
	v_max_f32_e32 v7, v30, v0
	v_min_f32_e32 v0, v30, v0
	v_max_f32_e32 v88, v18, v80
	v_min_f32_e32 v80, v18, v80
	v_max_f32_e32 v9, v3, v27
	v_min_f32_e32 v27, v3, v27
	v_max_f32_e32 v144, v28, v29
	v_min_f32_e32 v29, v28, v29
	v_max_f32_e32 v146, v7, v87
	v_min_f32_e32 v87, v7, v87
	v_max_f32_e32 v84, v0, v88
	v_min_f32_e32 v88, v0, v88
	v_max_f32_e32 v6, v90, v80
	v_min_f32_e32 v80, v90, v80
	v_max_f32_e32 v8, v29, v146
	v_min_f32_e32 v146, v29, v146
	v_max_f32_e32 v94, v87, v84
	v_min_f32_e32 v84, v87, v84
	v_max_f32_e32 v249, v48, v61
	v_min_f32_e32 v61, v48, v61
	v_max_f32_e32 v1, v49, v60
	v_min_f32_e32 v60, v49, v60
	v_max_f32_e32 v148, v50, v63
	v_min_f32_e32 v63, v50, v63
	v_max_f32_e32 v92, v51, v62
	v_min_f32_e32 v62, v51, v62
	v_max_f32_e32 v255, v52, v56
	v_min_f32_e32 v56, v52, v56
	v_max_f32_e32 v10, v53, v54
	v_min_f32_e32 v54, v53, v54
	v_max_f32_e32 v97, v55, v59
	v_min_f32_e32 v59, v55, v59
	v_max_f32_e32 v250, v57, v58
	v_min_f32_e32 v58, v57, v58
	v_max_f32_e32 v149, v249, v10
	v_min_f32_e32 v10, v249, v10
	v_max_f32_e32 v145, v1, v97
	v_min_f32_e32 v97, v1, v97
	v_max_f32_e32 v14, v148, v250
	v_min_f32_e32 v250, v148, v250
	v_max_f32_e32 v2, v92, v255
	v_min_f32_e32 v255, v92, v255
	v_max_f32_e32 v103, v54, v61
	v_min_f32_e32 v61, v54, v61
	v_max_f32_e32 v12, v56, v62
	v_min_f32_e32 v62, v56, v62
	v_max_f32_e32 v106, v58, v63
	v_min_f32_e32 v63, v58, v63
	v_max_f32_e32 v100, v59, v60
	v_min_f32_e32 v60, v59, v60
	v_max_f32_e32 v254, v149, v145
	v_min_f32_e32 v145, v149, v145
	v_max_f32_e32 v13, v14, v2
	v_min_f32_e32 v2, v14, v2
	v_max_f32_e32 v251, v255, v10
	v_min_f32_e32 v10, v255, v10
	v_max_f32_e32 v32, v103, v12
	v_min_f32_e32 v12, v103, v12
	v_max_f32_e32 v33, v97, v250
	v_min_f32_e32 v250, v97, v250
	v_max_f32_e32 v34, v106, v100
	v_min_f32_e32 v100, v106, v100
	v_max_f32_e32 v35, v60, v61
	v_min_f32_e32 v61, v60, v61
	v_max_f32_e32 v36, v62, v63
	v_min_f32_e32 v63, v62, v63
	v_max_f32_e32 v37, v254, v13
	v_min_f32_e32 v13, v254, v13
	v_max_f32_e32 v39, v145, v2
	v_min_f32_e32 v2, v145, v2
	v_max_f32_e32 v41, v251, v34
	v_min_f32_e32 v34, v251, v34
	v_max_f32_e32 v116, v10, v100
	v_min_f32_e32 v100, v10, v100
	v_max_f32_e32 v101, v32, v33
	v_min_f32_e32 v33, v32, v33
	v_max_f32_e32 v118, v12, v250
	v_min_f32_e32 v250, v12, v250
	v_max_f32_e32 v96, v35, v36
	v_min_f32_e32 v36, v35, v36
	v_max_f32_e32 v38, v61, v63
	v_min_f32_e32 v63, v61, v63
	v_max_f32_e32 v40, v39, v13
	v_min_f32_e32 v13, v39, v13
	v_max_f32_e32 v42, v2, v96
	v_min_f32_e32 v96, v2, v96
	v_max_f32_e32 v43, v41, v101
	v_min_f32_e32 v101, v41, v101
	v_max_f32_e32 v127, v116, v33
	v_min_f32_e32 v33, v116, v33
	v_max_f32_e32 v123, v118, v34
	v_min_f32_e32 v34, v118, v34
	v_max_f32_e32 v121, v250, v100
	v_min_f32_e32 v100, v250, v100
	v_max_f32_e32 v66, v38, v36
	v_min_f32_e32 v36, v38, v36
	v_max_f32_e32 v124, v40, v43
	v_min_f32_e32 v43, v40, v43
	v_max_f32_e32 v68, v13, v101
	v_min_f32_e32 v101, v13, v101
	v_max_f32_e32 v44, v127, v123
	v_min_f32_e32 v123, v127, v123
	v_max_f32_e32 v46, v33, v34
	v_min_f32_e32 v34, v33, v34
	v_max_f32_e32 v65, v121, v66
	v_min_f32_e32 v66, v121, v66
	v_max_f32_e32 v109, v100, v36
	v_min_f32_e32 v36, v100, v36
	v_max_f32_e32 v117, v68, v43
	v_min_f32_e32 v43, v68, v43
	v_max_f32_e32 v114, v42, v101
	v_min_f32_e32 v101, v42, v101
	v_max_f32_e32 v16, v65, v96
	v_min_f32_e32 v96, v65, v96
	v_max_f32_e32 v122, v109, v66
	v_min_f32_e32 v66, v109, v66
	v_max_f32_e32 v19, v114, v44
	v_min_f32_e32 v44, v114, v44
	v_max_f32_e32 v45, v101, v123
	v_min_f32_e32 v123, v101, v123
	v_max_f32_e32 v23, v46, v16
	v_min_f32_e32 v16, v46, v16
	v_max_f32_e32 v102, v34, v96
	v_min_f32_e32 v96, v34, v96
	v_max_f32_e32 v25, v19, v43
	v_min_f32_e32 v43, v19, v43
	v_max_f32_e32 v77, v44, v45
	v_min_f32_e32 v45, v44, v45
	v_max_f32_e32 v79, v23, v123
	v_min_f32_e32 v123, v23, v123
	v_max_f32_e32 v125, v16, v102
	v_min_f32_e32 v102, v16, v102
	v_max_f32_e32 v22, v122, v96
	v_min_f32_e32 v96, v122, v96
	v_max_f32_e32 v24, v45, v79
	v_min_f32_e32 v79, v45, v79
	v_max_f32_e32 v67, v123, v125
	v_min_f32_e32 v125, v123, v125
	v_max_f32_e32 v105, v105, v31
	v_max_f32_e32 v120, v120, v4
	v_max_f32_e32 v126, v126, v253
	v_max_f32_e32 v70, v70, v147
	v_max_f32_e32 v115, v115, v112
	v_max_f32_e32 v71, v71, v252
	v_max_f32_e32 v75, v75, v151
	v_max_f32_e32 v72, v72, v98
	v_max_f32_e32 v76, v76, v110
	v_max_f32_e32 v73, v73, v113
	v_max_f32_e32 v69, v69, v108
	v_max_f32_e32 v74, v74, v11
	v_max_f32_e32 v111, v111, v107
	v_max_f32_e32 v119, v119, v99
	v_max_f32_e32 v104, v104, v150
	v_max_f32_e32 v15, v15, v5
	v_max_f32_e32 v85, v105, v76
	v_min_f32_e32 v76, v105, v76
	v_max_f32_e32 v17, v120, v73
	v_min_f32_e32 v73, v120, v73
	v_max_f32_e32 v81, v126, v69
	v_min_f32_e32 v69, v126, v69
	v_max_f32_e32 v64, v70, v74
	v_min_f32_e32 v74, v70, v74
	v_max_f32_e32 v91, v115, v111
	v_min_f32_e32 v111, v115, v111
	v_max_f32_e32 v26, v71, v119
	v_min_f32_e32 v119, v71, v119
	v_max_f32_e32 v93, v75, v104
	v_min_f32_e32 v104, v75, v104
	v_max_f32_e32 v86, v72, v15
	v_min_f32_e32 v15, v72, v15
	v_max_f32_e32 v82, v85, v91
	v_min_f32_e32 v91, v85, v91
	v_max_f32_e32 v78, v17, v26
	v_min_f32_e32 v26, v17, v26
	v_max_f32_e32 v30, v81, v93
	v_min_f32_e32 v93, v81, v93
	v_max_f32_e32 v18, v64, v86
	v_min_f32_e32 v86, v64, v86
	v_max_f32_e32 v3, v76, v111
	v_min_f32_e32 v111, v76, v111
	v_max_f32_e32 v28, v73, v119
	v_min_f32_e32 v119, v73, v119
	v_max_f32_e32 v7, v69, v104
	v_min_f32_e32 v104, v69, v104
	v_max_f32_e32 v0, v74, v15
	v_min_f32_e32 v15, v74, v15
	v_max_f32_e32 v90, v82, v30
	v_min_f32_e32 v30, v82, v30
	v_max_f32_e32 v29, v78, v18
	v_min_f32_e32 v18, v78, v18
	v_max_f32_e32 v87, v91, v93
	v_min_f32_e32 v93, v91, v93
	v_max_f32_e32 v48, v26, v86
	v_min_f32_e32 v86, v26, v86
	v_max_f32_e32 v49, v3, v7
	v_min_f32_e32 v7, v3, v7
	v_max_f32_e32 v50, v28, v0
	v_min_f32_e32 v0, v28, v0
	v_max_f32_e32 v51, v111, v104
	v_min_f32_e32 v104, v111, v104
	v_max_f32_e32 v52, v119, v15
	v_min_f32_e32 v15, v119, v15
	v_max_f32_e32 v53, v90, v29
	v_min_f32_e32 v29, v90, v29
	v_max_f32_e32 v55, v30, v18
	v_min_f32_e32 v18, v30, v18
	v_max_f32_e32 v57, v87, v48
	v_min_f32_e32 v48, v87, v48
	v_max_f32_e32 v249, v93, v86
	v_min_f32_e32 v86, v93, v86
	v_max_f32_e32 v1, v49, v50
	v_min_f32_e32 v50, v49, v50
	v_max_f32_e32 v148, v7, v0
	v_min_f32_e32 v0, v7, v0
	v_max_f32_e32 v92, v51, v52
	v_min_f32_e32 v52, v51, v52
	v_max_f32_e32 v54, v104, v15
	v_min_f32_e32 v15, v104, v15
	v_max_f32_e32 v21, v21, v63
	v_max_f32_e32 v83, v83, v36
	v_max_f32_e32 v95, v95, v66
	v_max_f32_e32 v9, v9, v96
	v_max_f32_e32 v27, v27, v22
	v_max_f32_e32 v144, v144, v102
	v_max_f32_e32 v8, v8, v125
	v_max_f32_e32 v146, v146, v67
	v_max_f32_e32 v94, v94, v79
	v_max_f32_e32 v84, v84, v24
	v_max_f32_e32 v88, v88, v77
	v_max_f32_e32 v6, v6, v43
	v_max_f32_e32 v80, v80, v25
	v_max_f32_e32 v89, v89, v117
	v_max_f32_e32 v20, v20, v124
	v_max_f32_e32 v47, v47, v37
	v_max_f32_e32 v56, v21, v94
	v_min_f32_e32 v94, v21, v94
	v_max_f32_e32 v58, v83, v84
	v_min_f32_e32 v84, v83, v84
	v_max_f32_e32 v59, v95, v88
	v_min_f32_e32 v88, v95, v88
	v_max_f32_e32 v149, v9, v6
	v_min_f32_e32 v6, v9, v6
	v_max_f32_e32 v14, v27, v80
	v_min_f32_e32 v80, v27, v80
	v_max_f32_e32 v255, v144, v89
	v_min_f32_e32 v89, v144, v89
	v_max_f32_e32 v103, v8, v20
	v_min_f32_e32 v20, v8, v20
	v_max_f32_e32 v97, v146, v47
	v_min_f32_e32 v47, v146, v47
	v_max_f32_e32 v106, v56, v14
	v_min_f32_e32 v14, v56, v14
	v_max_f32_e32 v60, v58, v255
	v_min_f32_e32 v255, v58, v255
	v_max_f32_e32 v62, v59, v103
	v_min_f32_e32 v103, v59, v103
	v_max_f32_e32 v254, v149, v97
	v_min_f32_e32 v97, v149, v97
	v_max_f32_e32 v145, v94, v80
	v_min_f32_e32 v80, v94, v80
	v_max_f32_e32 v251, v84, v89
	v_min_f32_e32 v89, v84, v89
	v_max_f32_e32 v10, v88, v20
	v_min_f32_e32 v20, v88, v20
	v_max_f32_e32 v32, v6, v47
	v_min_f32_e32 v47, v6, v47
	v_max_f32_e32 v12, v106, v62
	v_min_f32_e32 v62, v106, v62
	v_max_f32_e32 v35, v60, v254
	v_min_f32_e32 v254, v60, v254
	v_max_f32_e32 v61, v14, v103
	v_min_f32_e32 v103, v14, v103
	v_max_f32_e32 v39, v255, v97
	v_min_f32_e32 v97, v255, v97
	v_max_f32_e32 v2, v145, v10
	v_min_f32_e32 v10, v145, v10
	v_max_f32_e32 v41, v251, v32
	v_min_f32_e32 v32, v251, v32
	v_max_f32_e32 v116, v80, v20
	v_min_f32_e32 v20, v80, v20
	v_max_f32_e32 v118, v89, v47
	v_min_f32_e32 v47, v89, v47
	v_max_f32_e32 v250, v12, v35
	v_min_f32_e32 v35, v12, v35
	v_max_f32_e32 v38, v62, v254
	v_min_f32_e32 v254, v62, v254
	v_max_f32_e32 v40, v61, v39
	v_min_f32_e32 v39, v61, v39
	v_max_f32_e32 v13, v103, v97
	v_min_f32_e32 v97, v103, v97
	v_max_f32_e32 v127, v2, v41
	v_min_f32_e32 v41, v2, v41
	v_max_f32_e32 v33, v10, v32
	v_min_f32_e32 v32, v10, v32
	v_max_f32_e32 v121, v116, v118
	v_min_f32_e32 v118, v116, v118
	v_max_f32_e32 v100, v20, v47
	v_min_f32_e32 v47, v20, v47
	v_max_f32_e32 v53, v53, v47
	v_max_f32_e32 v29, v29, v100
	v_max_f32_e32 v55, v55, v118
	v_max_f32_e32 v18, v18, v121
	v_max_f32_e32 v57, v57, v32
	v_max_f32_e32 v48, v48, v33
	v_max_f32_e32 v249, v249, v41
	v_max_f32_e32 v86, v86, v127
	v_max_f32_e32 v1, v1, v97
	v_max_f32_e32 v50, v50, v13
	v_max_f32_e32 v148, v148, v39
	v_max_f32_e32 v0, v0, v40
	v_max_f32_e32 v92, v92, v254
	v_max_f32_e32 v52, v52, v38
	v_max_f32_e32 v54, v54, v35
	v_max_f32_e32 v15, v15, v250
	v_max_f32_e32 v68, v53, v1
	v_min_f32_e32 v1, v53, v1
	v_max_f32_e32 v42, v29, v50
	v_min_f32_e32 v50, v29, v50
	v_max_f32_e32 v65, v55, v148
	v_min_f32_e32 v148, v55, v148
	v_max_f32_e32 v109, v18, v0
	v_min_f32_e32 v0, v18, v0
	v_max_f32_e32 v114, v57, v92
	v_min_f32_e32 v92, v57, v92
	v_max_f32_e32 v101, v48, v52
	v_min_f32_e32 v52, v48, v52
	v_max_f32_e32 v46, v249, v54
	v_min_f32_e32 v54, v249, v54
	v_max_f32_e32 v34, v86, v15
	v_min_f32_e32 v15, v86, v15
	v_max_f32_e32 v19, v68, v114
	v_min_f32_e32 v114, v68, v114
	v_max_f32_e32 v44, v42, v101
	v_min_f32_e32 v101, v42, v101
	v_max_f32_e32 v23, v65, v46
	v_min_f32_e32 v46, v65, v46
	v_max_f32_e32 v16, v109, v34
	v_min_f32_e32 v34, v109, v34
	v_max_f32_e32 v122, v1, v92
	v_min_f32_e32 v92, v1, v92
	v_max_f32_e32 v45, v50, v52
	v_min_f32_e32 v52, v50, v52
	v_max_f32_e32 v123, v148, v54
	v_min_f32_e32 v54, v148, v54
	v_max_f32_e32 v5, v0, v15
	v_min_f32_e32 v15, v0, v15
	v_max_f32_e32 v150, v19, v23
	v_min_f32_e32 v23, v19, v23
	v_max_f32_e32 v99, v44, v16
	v_min_f32_e32 v16, v44, v16
	v_max_f32_e32 v107, v114, v46
	v_min_f32_e32 v46, v114, v46
	v_max_f32_e32 v11, v101, v34
	v_min_f32_e32 v34, v101, v34
	v_max_f32_e32 v108, v122, v123
	v_min_f32_e32 v123, v122, v123
	v_max_f32_e32 v113, v45, v5
	v_min_f32_e32 v5, v45, v5
	v_max_f32_e32 v110, v92, v54
	v_min_f32_e32 v54, v92, v54
	v_max_f32_e32 v98, v52, v15
	v_min_f32_e32 v15, v52, v15
	v_max_f32_e32 v151, v150, v99
	v_min_f32_e32 v99, v150, v99
	v_max_f32_e32 v252, v23, v16
	v_min_f32_e32 v16, v23, v16
	v_max_f32_e32 v112, v107, v11
	v_min_f32_e32 v11, v107, v11
	v_max_f32_e32 v147, v46, v34
	v_min_f32_e32 v34, v46, v34
	v_max_f32_e32 v253, v108, v113
	v_min_f32_e32 v113, v108, v113
	v_max_f32_e32 v4, v123, v5
	v_min_f32_e32 v5, v123, v5
	v_max_f32_e32 v31, v110, v98
	v_min_f32_e32 v98, v110, v98
	v_max_f32_e32 v105, v54, v15
	v_min_f32_e32 v15, v54, v15
	v_mov_b32_e32 v120, v151
	v_mov_b32_e32 v126, v99
	v_mov_b32_e32 v70, v252
	v_mov_b32_e32 v115, v16
	v_mov_b32_e32 v71, v112
	v_mov_b32_e32 v75, v11
	v_mov_b32_e32 v72, v147
	v_mov_b32_e32 v85, v34
	v_mov_b32_e32 v17, v253
	v_mov_b32_e32 v81, v113
	v_mov_b32_e32 v64, v4
	v_mov_b32_e32 v76, v5
	v_mov_b32_e32 v73, v31
	v_mov_b32_e32 v69, v98
	v_mov_b32_e32 v74, v105
	v_mov_b32_e32 v82, v15
	s_nop 1
	v_permlane32_swap_b32_e32 v151, v120
	v_permlane32_swap_b32_e32 v99, v126
	v_permlane32_swap_b32_e32 v252, v70
	v_permlane32_swap_b32_e32 v16, v115
	v_permlane32_swap_b32_e32 v112, v71
	v_permlane32_swap_b32_e32 v11, v75
	v_permlane32_swap_b32_e32 v147, v72
	v_permlane32_swap_b32_e32 v34, v85
	v_permlane32_swap_b32_e32 v253, v17
	v_permlane32_swap_b32_e32 v113, v81
	v_permlane32_swap_b32_e32 v4, v64
	v_permlane32_swap_b32_e32 v5, v76
	v_permlane32_swap_b32_e32 v31, v73
	v_permlane32_swap_b32_e32 v98, v69
	v_permlane32_swap_b32_e32 v105, v74
	v_permlane32_swap_b32_e32 v15, v82
	s_nop 1
	v_max_f32_e32 v151, v151, v82
	v_max_f32_e32 v99, v99, v74
	v_max_f32_e32 v252, v252, v69
	v_max_f32_e32 v16, v16, v73
	v_max_f32_e32 v112, v112, v76
	v_max_f32_e32 v11, v11, v64
	v_max_f32_e32 v147, v147, v81
	v_max_f32_e32 v34, v34, v17
	v_max_f32_e32 v253, v253, v85
	v_max_f32_e32 v113, v113, v72
	v_max_f32_e32 v4, v4, v75
	v_max_f32_e32 v5, v5, v71
	v_max_f32_e32 v31, v31, v115
	v_max_f32_e32 v98, v98, v70
	v_max_f32_e32 v105, v105, v126
	v_max_f32_e32 v15, v15, v120
	v_max_f32_e32 v78, v151, v253
	v_min_f32_e32 v253, v151, v253
	v_max_f32_e32 v91, v99, v113
	v_min_f32_e32 v113, v99, v113
	v_max_f32_e32 v26, v252, v4
	v_min_f32_e32 v4, v252, v4
	v_max_f32_e32 v3, v16, v5
	v_min_f32_e32 v5, v16, v5
	v_max_f32_e32 v28, v112, v31
	v_min_f32_e32 v31, v112, v31
	v_max_f32_e32 v111, v11, v98
	v_min_f32_e32 v98, v11, v98
	v_max_f32_e32 v119, v147, v105
	v_min_f32_e32 v105, v147, v105
	v_max_f32_e32 v90, v34, v15
	v_min_f32_e32 v15, v34, v15
	v_max_f32_e32 v30, v78, v28
	v_min_f32_e32 v28, v78, v28
	v_max_f32_e32 v87, v91, v111
	v_min_f32_e32 v111, v91, v111
	v_max_f32_e32 v93, v26, v119
	v_min_f32_e32 v119, v26, v119
	v_max_f32_e32 v49, v3, v90
	v_min_f32_e32 v90, v3, v90
	v_max_f32_e32 v7, v253, v31
	v_min_f32_e32 v31, v253, v31
	v_max_f32_e32 v51, v113, v98
	v_min_f32_e32 v98, v113, v98
	v_max_f32_e32 v104, v4, v105
	v_min_f32_e32 v105, v4, v105
	v_max_f32_e32 v37, v5, v15
	v_min_f32_e32 v15, v5, v15
	v_max_f32_e32 v124, v30, v93
	v_min_f32_e32 v93, v30, v93
	v_max_f32_e32 v117, v87, v49
	v_min_f32_e32 v49, v87, v49
	v_max_f32_e32 v25, v28, v119
	v_min_f32_e32 v119, v28, v119
	v_max_f32_e32 v43, v111, v90
	v_min_f32_e32 v90, v111, v90
	v_max_f32_e32 v77, v7, v104
	v_min_f32_e32 v104, v7, v104
	v_max_f32_e32 v24, v51, v37
	v_min_f32_e32 v37, v51, v37
	v_max_f32_e32 v79, v31, v105
	v_min_f32_e32 v105, v31, v105
	v_max_f32_e32 v67, v98, v15
	v_min_f32_e32 v15, v98, v15
	v_max_f32_e32 v125, v124, v117
	v_min_f32_e32 v117, v124, v117
	v_max_f32_e32 v102, v93, v49
	v_min_f32_e32 v49, v93, v49
	v_max_f32_e32 v22, v25, v43
	v_min_f32_e32 v43, v25, v43
	v_max_f32_e32 v96, v119, v90
	v_min_f32_e32 v90, v119, v90
	v_max_f32_e32 v66, v77, v24
	v_min_f32_e32 v24, v77, v24
	v_max_f32_e32 v36, v104, v37
	v_min_f32_e32 v37, v104, v37
	v_max_f32_e32 v63, v79, v67
	v_min_f32_e32 v67, v79, v67
	v_max_f32_e32 v21, v105, v15
	v_min_f32_e32 v15, v105, v15
	ds_write_b8 v240, v125 offset:512
	ds_write_b8 v240, v117 offset:513
	ds_write_b8 v240, v102 offset:514
	ds_write_b8 v240, v49 offset:515
	ds_write_b8 v240, v22 offset:516
	ds_write_b8 v240, v43 offset:517
	ds_write_b8 v240, v96 offset:518
	ds_write_b8 v240, v90 offset:519
	ds_write_b8 v240, v66 offset:520
	ds_write_b8 v240, v24 offset:521
	ds_write_b8 v240, v36 offset:522
	ds_write_b8 v240, v37 offset:523
	ds_write_b8 v240, v63 offset:524
	ds_write_b8 v240, v67 offset:525
	ds_write_b8 v240, v21 offset:526
	ds_write_b8 v240, v15 offset:527
	v_cndmask_b32_e64 v0, v128, v125, s[4:5]
	v_cndmask_b32_e64 v17, v125, v128, s[4:5]
	v_cndmask_b32_e64 v1, v129, v117, s[4:5]
	v_cndmask_b32_e64 v18, v117, v129, s[4:5]
	v_cndmask_b32_e64 v2, v130, v102, s[4:5]
	v_cndmask_b32_e64 v19, v102, v130, s[4:5]
	v_cndmask_b32_e64 v3, v131, v49, s[4:5]
	v_cndmask_b32_e64 v20, v49, v131, s[4:5]
	v_cndmask_b32_e64 v4, v132, v22, s[4:5]
	v_cndmask_b32_e64 v23, v22, v132, s[4:5]
	v_cndmask_b32_e64 v5, v133, v43, s[4:5]
	v_cndmask_b32_e64 v25, v43, v133, s[4:5]
	v_cndmask_b32_e64 v6, v134, v96, s[4:5]
	v_cndmask_b32_e64 v26, v96, v134, s[4:5]
	v_cndmask_b32_e64 v7, v135, v90, s[4:5]
	v_cndmask_b32_e64 v27, v90, v135, s[4:5]
	v_cndmask_b32_e64 v8, v136, v66, s[4:5]
	v_cndmask_b32_e64 v28, v66, v136, s[4:5]
	v_cndmask_b32_e64 v9, v137, v24, s[4:5]
	v_cndmask_b32_e64 v29, v24, v137, s[4:5]
	v_cndmask_b32_e64 v10, v138, v36, s[4:5]
	v_cndmask_b32_e64 v30, v36, v138, s[4:5]
	v_cndmask_b32_e64 v11, v139, v37, s[4:5]
	v_cndmask_b32_e64 v31, v37, v139, s[4:5]
	v_cndmask_b32_e64 v12, v140, v63, s[4:5]
	v_cndmask_b32_e64 v32, v63, v140, s[4:5]
	v_cndmask_b32_e64 v13, v141, v67, s[4:5]
	v_cndmask_b32_e64 v33, v67, v141, s[4:5]
	v_cndmask_b32_e64 v14, v142, v21, s[4:5]
	v_cndmask_b32_e64 v34, v21, v142, s[4:5]
	v_cndmask_b32_e64 v16, v143, v15, s[4:5]
	v_cndmask_b32_e64 v35, v15, v143, s[4:5]
	v_and_b32_e32 v0, s6, v0
	v_and_b32_e32 v17, s6, v17
	v_and_b32_e32 v1, s6, v1
	v_and_b32_e32 v18, s6, v18
	v_and_b32_e32 v2, s6, v2
	v_and_b32_e32 v19, s6, v19
	v_and_b32_e32 v3, s6, v3
	v_and_b32_e32 v20, s6, v20
	v_and_b32_e32 v4, s6, v4
	v_and_b32_e32 v23, s6, v23
	v_and_b32_e32 v5, s6, v5
	v_and_b32_e32 v25, s6, v25
	v_and_b32_e32 v6, s6, v6
	v_and_b32_e32 v26, s6, v26
	v_and_b32_e32 v7, s6, v7
	v_and_b32_e32 v27, s6, v27
	v_and_b32_e32 v8, s6, v8
	v_and_b32_e32 v28, s6, v28
	v_and_b32_e32 v9, s6, v9
	v_and_b32_e32 v29, s6, v29
	v_and_b32_e32 v10, s6, v10
	v_and_b32_e32 v30, s6, v30
	v_and_b32_e32 v11, s6, v11
	v_and_b32_e32 v31, s6, v31
	v_and_b32_e32 v12, s6, v12
	v_and_b32_e32 v32, s6, v32
	v_and_b32_e32 v13, s6, v13
	v_and_b32_e32 v33, s6, v33
	v_and_b32_e32 v14, s6, v14
	v_and_b32_e32 v34, s6, v34
	v_and_b32_e32 v16, s6, v16
	v_and_b32_e32 v35, s6, v35
	v_add_f32_e32 v38, v0, v18
	v_and_or_b32 v38, v38, s7, 0
	v_add_f32_e32 v39, v0, v19
	v_and_or_b32 v39, v39, s7, 2
	v_add_f32_e32 v40, v0, v20
	v_and_or_b32 v40, v40, s7, 4
	v_add_f32_e32 v41, v0, v23
	v_and_or_b32 v41, v41, s7, 6
	v_add_f32_e32 v42, v0, v25
	v_and_or_b32 v42, v42, s7, 8
	v_add_f32_e32 v44, v0, v26
	v_and_or_b32 v44, v44, s7, 10
	v_add_f32_e32 v45, v0, v27
	v_and_or_b32 v45, v45, s7, 12
	v_add_f32_e32 v46, v0, v28
	v_and_or_b32 v46, v46, s7, 14
	v_add_f32_e32 v47, v0, v29
	v_and_or_b32 v47, v47, s7, 16
	v_add_f32_e32 v48, v0, v30
	v_and_or_b32 v48, v48, s7, 18
	v_add_f32_e32 v50, v0, v31
	v_and_or_b32 v50, v50, s7, 20
	v_add_f32_e32 v51, v0, v32
	v_and_or_b32 v51, v51, s7, 22
	v_add_f32_e32 v52, v0, v33
	v_and_or_b32 v52, v52, s7, 24
	v_add_f32_e32 v53, v0, v34
	v_and_or_b32 v53, v53, s7, 26
	v_add_f32_e32 v54, v0, v35
	v_and_or_b32 v54, v54, s7, 28
	v_add_f32_e32 v55, v1, v19
	v_and_or_b32 v55, v55, s7, 30
	v_add_f32_e32 v56, v1, v20
	v_and_or_b32 v56, v56, s7, 32
	v_add_f32_e32 v57, v1, v23
	v_and_or_b32 v57, v57, s7, 34
	v_add_f32_e32 v58, v1, v25
	v_and_or_b32 v58, v58, s7, 36
	v_add_f32_e32 v59, v1, v26
	v_and_or_b32 v59, v59, s7, 38
	v_add_f32_e32 v60, v1, v27
	v_and_or_b32 v60, v60, s7, 40
	v_add_f32_e32 v61, v2, v20
	v_and_or_b32 v61, v61, s7, 42
	v_add_f32_e32 v62, v2, v23
	v_and_or_b32 v62, v62, s7, 44
	v_add_f32_e32 v64, v0, v17
	v_and_or_b32 v64, v64, s7, 46
	v_cndmask_b32_e64 v64, v64, v244, s[4:5]
	v_add_f32_e32 v65, v1, v18
	v_and_or_b32 v65, v65, s7, 48
	v_cndmask_b32_e64 v65, v65, v244, s[4:5]
	v_add_f32_e32 v68, v2, v19
	v_and_or_b32 v68, v68, s7, 50
	v_cndmask_b32_e64 v68, v68, v244, s[4:5]
	v_add_f32_e32 v69, v3, v20
	v_and_or_b32 v69, v69, s7, 52
	v_cndmask_b32_e64 v69, v69, v244, s[4:5]
	v_max_f32_e32 v70, v38, v53
	v_min_f32_e32 v53, v38, v53
	v_max_f32_e32 v71, v39, v52
	v_min_f32_e32 v52, v39, v52
	v_max_f32_e32 v72, v40, v55
	v_min_f32_e32 v55, v40, v55
	v_max_f32_e32 v73, v41, v54
	v_min_f32_e32 v54, v41, v54
	v_max_f32_e32 v74, v42, v47
	v_min_f32_e32 v47, v42, v47
	v_max_f32_e32 v75, v44, v45
	v_min_f32_e32 v45, v44, v45
	v_max_f32_e32 v76, v46, v51
	v_min_f32_e32 v51, v46, v51
	v_max_f32_e32 v77, v48, v50
	v_min_f32_e32 v50, v48, v50
	v_max_f32_e32 v78, v70, v75
	v_min_f32_e32 v75, v70, v75
	v_max_f32_e32 v79, v71, v76
	v_min_f32_e32 v76, v71, v76
	v_max_f32_e32 v80, v72, v77
	v_min_f32_e32 v77, v72, v77
	v_max_f32_e32 v81, v73, v74
	v_min_f32_e32 v74, v73, v74
	v_max_f32_e32 v82, v45, v53
	v_min_f32_e32 v53, v45, v53
	v_max_f32_e32 v83, v47, v54
	v_min_f32_e32 v54, v47, v54
	v_max_f32_e32 v84, v50, v55
	v_min_f32_e32 v55, v50, v55
	v_max_f32_e32 v85, v51, v52
	v_min_f32_e32 v52, v51, v52
	v_max_f32_e32 v86, v78, v79
	v_min_f32_e32 v79, v78, v79
	v_max_f32_e32 v87, v80, v81
	v_min_f32_e32 v81, v80, v81
	v_max_f32_e32 v88, v74, v75
	v_min_f32_e32 v75, v74, v75
	v_max_f32_e32 v89, v82, v83
	v_min_f32_e32 v83, v82, v83
	v_max_f32_e32 v91, v76, v77
	v_min_f32_e32 v77, v76, v77
	v_max_f32_e32 v92, v84, v85
	v_min_f32_e32 v85, v84, v85
	v_max_f32_e32 v93, v52, v53
	v_min_f32_e32 v53, v52, v53
	v_max_f32_e32 v94, v54, v55
	v_min_f32_e32 v55, v54, v55
	v_max_f32_e32 v95, v86, v87
	v_min_f32_e32 v87, v86, v87
	v_max_f32_e32 v97, v79, v81
	v_min_f32_e32 v81, v79, v81
	v_max_f32_e32 v98, v88, v92
	v_min_f32_e32 v92, v88, v92
	v_max_f32_e32 v99, v75, v85
	v_min_f32_e32 v85, v75, v85
	v_max_f32_e32 v100, v89, v91
	v_min_f32_e32 v91, v89, v91
	v_max_f32_e32 v101, v83, v77
	v_min_f32_e32 v77, v83, v77
	v_max_f32_e32 v103, v93, v94
	v_min_f32_e32 v94, v93, v94
	v_max_f32_e32 v104, v53, v55
	v_min_f32_e32 v55, v53, v55
	v_max_f32_e32 v105, v97, v87
	v_min_f32_e32 v87, v97, v87
	v_max_f32_e32 v106, v81, v103
	v_min_f32_e32 v103, v81, v103
	v_max_f32_e32 v107, v98, v100
	v_min_f32_e32 v100, v98, v100
	v_max_f32_e32 v108, v99, v91
	v_min_f32_e32 v91, v99, v91
	v_max_f32_e32 v109, v101, v92
	v_min_f32_e32 v92, v101, v92
	v_max_f32_e32 v110, v77, v85
	v_min_f32_e32 v85, v77, v85
	v_max_f32_e32 v111, v104, v94
	v_min_f32_e32 v94, v104, v94
	v_max_f32_e32 v112, v105, v107
	v_min_f32_e32 v107, v105, v107
	v_max_f32_e32 v113, v87, v100
	v_min_f32_e32 v100, v87, v100
	v_max_f32_e32 v114, v108, v109
	v_min_f32_e32 v109, v108, v109
	v_max_f32_e32 v115, v91, v92
	v_min_f32_e32 v92, v91, v92
	v_max_f32_e32 v116, v110, v111
	v_min_f32_e32 v111, v110, v111
	v_max_f32_e32 v118, v85, v94
	v_min_f32_e32 v94, v85, v94
	v_max_f32_e32 v119, v113, v107
	v_min_f32_e32 v107, v113, v107
	v_max_f32_e32 v120, v106, v100
	v_min_f32_e32 v100, v106, v100
	v_max_f32_e32 v121, v116, v103
	v_min_f32_e32 v103, v116, v103
	v_max_f32_e32 v122, v118, v111
	v_min_f32_e32 v111, v118, v111
	v_max_f32_e32 v123, v120, v114
	v_min_f32_e32 v114, v120, v114
	v_max_f32_e32 v124, v100, v109
	v_min_f32_e32 v109, v100, v109
	v_max_f32_e32 v126, v115, v121
	v_min_f32_e32 v121, v115, v121
	v_max_f32_e32 v127, v92, v103
	v_min_f32_e32 v103, v92, v103
	v_max_f32_e32 v144, v123, v107
	v_min_f32_e32 v107, v123, v107
	v_max_f32_e32 v145, v114, v124
	v_min_f32_e32 v124, v114, v124
	v_max_f32_e32 v146, v126, v109
	v_min_f32_e32 v109, v126, v109
	v_max_f32_e32 v147, v121, v127
	v_min_f32_e32 v127, v121, v127
	v_max_f32_e32 v148, v122, v103
	v_min_f32_e32 v103, v122, v103
	v_max_f32_e32 v149, v124, v146
	v_min_f32_e32 v146, v124, v146
	v_max_f32_e32 v150, v109, v147
	v_min_f32_e32 v147, v109, v147
	v_max_f32_e32 v151, v60, v65
	v_min_f32_e32 v65, v60, v65
	v_max_f32_e32 v249, v61, v62
	v_min_f32_e32 v62, v61, v62
	v_max_f32_e32 v250, v68, v69
	v_min_f32_e32 v69, v68, v69
	v_max_f32_e32 v251, v56, v249
	v_min_f32_e32 v249, v56, v249
	v_max_f32_e32 v252, v57, v64
	v_min_f32_e32 v64, v57, v64
	v_max_f32_e32 v253, v58, v250
	v_min_f32_e32 v250, v58, v250
	v_max_f32_e32 v254, v59, v151
	v_min_f32_e32 v151, v59, v151
	v_max_f32_e32 v255, v251, v252
	v_min_f32_e32 v252, v251, v252
	v_max_f32_e32 v128, v253, v254
	v_min_f32_e32 v254, v253, v254
	v_max_f32_e32 v129, v151, v249
	v_min_f32_e32 v249, v151, v249
	v_max_f32_e32 v130, v62, v65
	v_min_f32_e32 v65, v62, v65
	v_max_f32_e32 v131, v64, v250
	v_min_f32_e32 v250, v64, v250
	v_max_f32_e32 v132, v255, v128
	v_min_f32_e32 v128, v255, v128
	v_max_f32_e32 v133, v252, v254
	v_min_f32_e32 v254, v252, v254
	v_max_f32_e32 v134, v129, v69
	v_min_f32_e32 v69, v129, v69
	v_max_f32_e32 v135, v130, v131
	v_min_f32_e32 v131, v130, v131
	v_max_f32_e32 v136, v65, v250
	v_min_f32_e32 v250, v65, v250
	v_max_f32_e32 v137, v133, v128
	v_min_f32_e32 v128, v133, v128
	v_max_f32_e32 v138, v134, v135
	v_min_f32_e32 v135, v134, v135
	v_max_f32_e32 v139, v249, v131
	v_min_f32_e32 v131, v249, v131
	v_max_f32_e32 v140, v136, v69
	v_min_f32_e32 v69, v136, v69
	v_max_f32_e32 v141, v137, v138
	v_min_f32_e32 v138, v137, v138
	v_max_f32_e32 v142, v128, v135
	v_min_f32_e32 v135, v128, v135
	v_max_f32_e32 v143, v139, v140
	v_min_f32_e32 v140, v139, v140
	v_max_f32_e32 v125, v131, v69
	v_min_f32_e32 v69, v131, v69
	v_max_f32_e32 v117, v142, v138
	v_min_f32_e32 v138, v142, v138
	v_max_f32_e32 v102, v254, v135
	v_min_f32_e32 v135, v254, v135
	v_max_f32_e32 v49, v102, v143
	v_min_f32_e32 v143, v102, v143
	v_max_f32_e32 v22, v135, v140
	v_min_f32_e32 v140, v135, v140
	v_max_f32_e32 v43, v125, v250
	v_min_f32_e32 v250, v125, v250
	v_max_f32_e32 v96, v49, v138
	v_min_f32_e32 v138, v49, v138
	v_max_f32_e32 v90, v143, v22
	v_min_f32_e32 v22, v143, v22
	v_max_f32_e32 v66, v43, v140
	v_min_f32_e32 v140, v43, v140
	v_max_f32_e32 v24, v250, v69
	v_min_f32_e32 v69, v250, v69
	v_max_f32_e32 v36, v22, v66
	v_min_f32_e32 v66, v22, v66
	v_max_f32_e32 v37, v140, v24
	v_min_f32_e32 v24, v140, v24
	v_max_f32_e32 v145, v145, v69
	v_max_f32_e32 v149, v149, v24
	v_max_f32_e32 v146, v146, v37
	v_max_f32_e32 v150, v150, v66
	v_max_f32_e32 v147, v147, v36
	v_max_f32_e32 v127, v127, v90
	v_max_f32_e32 v148, v148, v138
	v_max_f32_e32 v103, v103, v96
	v_max_f32_e32 v111, v111, v117
	v_max_f32_e32 v94, v94, v141
	v_max_f32_e32 v55, v55, v132
	v_max_f32_e32 v63, v95, v150
	v_min_f32_e32 v150, v95, v150
	v_max_f32_e32 v67, v112, v147
	v_min_f32_e32 v147, v112, v147
	v_max_f32_e32 v21, v119, v127
	v_min_f32_e32 v127, v119, v127
	v_max_f32_e32 v15, v144, v148
	v_min_f32_e32 v148, v144, v148
	v_max_f32_e32 v0, v107, v103
	v_min_f32_e32 v103, v107, v103
	v_max_f32_e32 v1, v145, v111
	v_min_f32_e32 v111, v145, v111
	v_max_f32_e32 v2, v149, v94
	v_min_f32_e32 v94, v149, v94
	v_max_f32_e32 v3, v146, v55
	v_min_f32_e32 v55, v146, v55
	v_max_f32_e32 v4, v63, v0
	v_min_f32_e32 v0, v63, v0
	v_max_f32_e32 v5, v67, v1
	v_min_f32_e32 v1, v67, v1
	v_max_f32_e32 v6, v21, v2
	v_min_f32_e32 v2, v21, v2
	v_max_f32_e32 v7, v15, v3
	v_min_f32_e32 v3, v15, v3
	v_max_f32_e32 v8, v150, v103
	v_min_f32_e32 v103, v150, v103
	v_max_f32_e32 v9, v147, v111
	v_min_f32_e32 v111, v147, v111
	v_max_f32_e32 v10, v127, v94
	v_min_f32_e32 v94, v127, v94
	v_max_f32_e32 v11, v148, v55
	v_min_f32_e32 v55, v148, v55
	v_max_f32_e32 v12, v4, v6
	v_min_f32_e32 v6, v4, v6
	v_max_f32_e32 v13, v5, v7
	v_min_f32_e32 v7, v5, v7
	v_max_f32_e32 v14, v0, v2
	v_min_f32_e32 v2, v0, v2
	v_max_f32_e32 v16, v1, v3
	v_min_f32_e32 v3, v1, v3
	v_max_f32_e32 v17, v8, v10
	v_min_f32_e32 v10, v8, v10
	v_max_f32_e32 v18, v9, v11
	v_min_f32_e32 v11, v9, v11
	v_max_f32_e32 v19, v103, v94
	v_min_f32_e32 v94, v103, v94
	v_max_f32_e32 v20, v111, v55
	v_min_f32_e32 v55, v111, v55
	v_max_f32_e32 v23, v12, v13
	v_min_f32_e32 v13, v12, v13
	v_max_f32_e32 v25, v6, v7
	v_min_f32_e32 v7, v6, v7
	v_max_f32_e32 v26, v14, v16
	v_min_f32_e32 v16, v14, v16
	v_max_f32_e32 v27, v2, v3
	v_min_f32_e32 v3, v2, v3
	v_max_f32_e32 v28, v17, v18
	v_min_f32_e32 v18, v17, v18
	v_max_f32_e32 v29, v10, v11
	v_min_f32_e32 v11, v10, v11
	v_max_f32_e32 v30, v19, v20
	v_min_f32_e32 v20, v19, v20
	v_max_f32_e32 v31, v94, v55
	v_min_f32_e32 v55, v94, v55
	v_or_b32_e32 v23, v23, v245
	v_or_b32_e32 v13, v13, v245
	v_or_b32_e32 v25, v25, v245
	v_or_b32_e32 v7, v7, v245
	v_or_b32_e32 v26, v26, v245
	v_or_b32_e32 v16, v16, v245
	v_or_b32_e32 v27, v27, v245
	v_or_b32_e32 v3, v3, v245
	v_or_b32_e32 v28, v28, v245
	v_or_b32_e32 v18, v18, v245
	v_or_b32_e32 v29, v29, v245
	v_or_b32_e32 v11, v11, v245
	v_or_b32_e32 v30, v30, v245
	v_or_b32_e32 v20, v20, v245
	v_or_b32_e32 v31, v31, v245
	v_or_b32_e32 v55, v55, v245
	v_mov_b32_e32 v32, v23
	v_mov_b32_e32 v33, v13
	v_mov_b32_e32 v34, v25
	v_mov_b32_e32 v35, v7
	v_mov_b32_e32 v38, v26
	v_mov_b32_e32 v39, v16
	v_mov_b32_e32 v40, v27
	v_mov_b32_e32 v41, v3
	v_mov_b32_e32 v42, v28
	v_mov_b32_e32 v44, v18
	v_mov_b32_e32 v46, v29
	v_mov_b32_e32 v48, v11
	v_mov_b32_e32 v70, v30
	v_mov_b32_e32 v71, v20
	v_mov_b32_e32 v72, v31
	v_mov_b32_e32 v73, v55
	s_nop 1
	v_permlane32_swap_b32_e32 v23, v32
	v_permlane32_swap_b32_e32 v13, v33
	v_permlane32_swap_b32_e32 v25, v34
	v_permlane32_swap_b32_e32 v7, v35
	v_permlane32_swap_b32_e32 v26, v38
	v_permlane32_swap_b32_e32 v16, v39
	v_permlane32_swap_b32_e32 v27, v40
	v_permlane32_swap_b32_e32 v3, v41
	v_permlane32_swap_b32_e32 v28, v42
	v_permlane32_swap_b32_e32 v18, v44
	v_permlane32_swap_b32_e32 v29, v46
	v_permlane32_swap_b32_e32 v11, v48
	v_permlane32_swap_b32_e32 v30, v70
	v_permlane32_swap_b32_e32 v20, v71
	v_permlane32_swap_b32_e32 v31, v72
	v_permlane32_swap_b32_e32 v55, v73
	s_nop 1
	v_max_f32_e32 v23, v23, v73
	v_max_f32_e32 v13, v13, v72
	v_max_f32_e32 v25, v25, v71
	v_max_f32_e32 v7, v7, v70
	v_max_f32_e32 v26, v26, v48
	v_max_f32_e32 v16, v16, v46
	v_max_f32_e32 v27, v27, v44
	v_max_f32_e32 v3, v3, v42
	v_max_f32_e32 v28, v28, v41
	v_max_f32_e32 v18, v18, v40
	v_max_f32_e32 v29, v29, v39
	v_max_f32_e32 v11, v11, v38
	v_max_f32_e32 v30, v30, v35
	v_max_f32_e32 v20, v20, v34
	v_max_f32_e32 v31, v31, v33
	v_max_f32_e32 v55, v55, v32
	v_max_f32_e32 v45, v23, v28
	v_min_f32_e32 v28, v23, v28
	v_max_f32_e32 v47, v13, v18
	v_min_f32_e32 v18, v13, v18
	v_max_f32_e32 v50, v25, v29
	v_min_f32_e32 v29, v25, v29
	v_max_f32_e32 v51, v7, v11
	v_min_f32_e32 v11, v7, v11
	v_max_f32_e32 v78, v26, v30
	v_min_f32_e32 v30, v26, v30
	v_max_f32_e32 v80, v16, v20
	v_min_f32_e32 v20, v16, v20
	v_max_f32_e32 v74, v27, v31
	v_min_f32_e32 v31, v27, v31
	v_max_f32_e32 v82, v3, v55
	v_min_f32_e32 v55, v3, v55
	v_max_f32_e32 v76, v45, v78
	v_min_f32_e32 v78, v45, v78
	v_max_f32_e32 v84, v47, v80
	v_min_f32_e32 v80, v47, v80
	v_max_f32_e32 v52, v50, v74
	v_min_f32_e32 v74, v50, v74
	v_max_f32_e32 v54, v51, v82
	v_min_f32_e32 v82, v51, v82
	v_max_f32_e32 v86, v28, v30
	v_min_f32_e32 v30, v28, v30
	v_max_f32_e32 v79, v18, v20
	v_min_f32_e32 v20, v18, v20
	v_max_f32_e32 v88, v29, v31
	v_min_f32_e32 v31, v29, v31
	v_max_f32_e32 v75, v11, v55
	v_min_f32_e32 v55, v11, v55
	v_max_f32_e32 v89, v76, v52
	v_min_f32_e32 v52, v76, v52
	v_max_f32_e32 v83, v84, v54
	v_min_f32_e32 v54, v84, v54
	v_max_f32_e32 v93, v78, v74
	v_min_f32_e32 v74, v78, v74
	v_max_f32_e32 v53, v80, v82
	v_min_f32_e32 v82, v80, v82
	v_max_f32_e32 v97, v86, v88
	v_min_f32_e32 v88, v86, v88
	v_max_f32_e32 v81, v79, v75
	v_min_f32_e32 v75, v79, v75
	v_max_f32_e32 v98, v30, v31
	v_min_f32_e32 v31, v30, v31
	v_max_f32_e32 v99, v20, v55
	v_min_f32_e32 v55, v20, v55
	v_max_f32_e32 v101, v89, v83
	v_min_f32_e32 v83, v89, v83
	v_max_f32_e32 v77, v52, v54
	v_min_f32_e32 v54, v52, v54
	v_max_f32_e32 v104, v93, v53
	v_min_f32_e32 v53, v93, v53
	v_max_f32_e32 v105, v74, v82
	v_min_f32_e32 v82, v74, v82
	v_max_f32_e32 v87, v97, v81
	v_min_f32_e32 v81, v97, v81
	v_max_f32_e32 v108, v88, v75
	v_min_f32_e32 v75, v88, v75
	v_max_f32_e32 v91, v98, v99
	v_min_f32_e32 v99, v98, v99
	v_max_f32_e32 v110, v31, v55
	v_min_f32_e32 v55, v31, v55
	v_and_b32_e32 v85, s7, v101
	v_cndmask_b32_e64 v113, v101, v87, s[4:5]
	v_cndmask_b32_e64 v106, v83, v81, s[4:5]
	v_cndmask_b32_e64 v116, v77, v108, s[4:5]
	v_cndmask_b32_e64 v118, v54, v75, s[4:5]
	v_cndmask_b32_e64 v120, v104, v91, s[4:5]
	v_cndmask_b32_e64 v100, v53, v99, s[4:5]
	v_cndmask_b32_e64 v115, v105, v110, s[4:5]
	v_cndmask_b32_e64 v92, v82, v55, s[4:5]
	v_and_or_b32 v123, v113, 63, v246
	ds_read_u8 v123, v123
	v_and_or_b32 v114, v106, 63, v246
	ds_read_u8 v114, v114
	v_and_or_b32 v126, v116, 63, v246
	ds_read_u8 v126, v126
	v_and_or_b32 v121, v118, 63, v246
	ds_read_u8 v121, v121
	v_and_or_b32 v122, v120, 63, v246
	ds_read_u8 v122, v122
	v_and_or_b32 v124, v100, 63, v246
	ds_read_u8 v124, v124
	v_and_or_b32 v109, v115, 63, v246
	ds_read_u8 v109, v109
	v_and_or_b32 v60, v92, 63, v246
	ds_read_u8 v60, v60
	v_and_b32_e32 v113, s7, v113
	v_sub_f32_e32 v113, v113, v85
	v_mul_f32_e32 v113, 0x3fb8aa3b, v113
	v_exp_f32_e32 v113, v113
	v_and_b32_e32 v106, s7, v106
	v_sub_f32_e32 v106, v106, v85
	v_mul_f32_e32 v106, 0x3fb8aa3b, v106
	v_exp_f32_e32 v106, v106
	v_and_b32_e32 v116, s7, v116
	v_sub_f32_e32 v116, v116, v85
	v_mul_f32_e32 v116, 0x3fb8aa3b, v116
	v_exp_f32_e32 v116, v116
	v_and_b32_e32 v118, s7, v118
	v_sub_f32_e32 v118, v118, v85
	v_mul_f32_e32 v118, 0x3fb8aa3b, v118
	v_exp_f32_e32 v118, v118
	v_and_b32_e32 v120, s7, v120
	v_sub_f32_e32 v120, v120, v85
	v_mul_f32_e32 v120, 0x3fb8aa3b, v120
	v_exp_f32_e32 v120, v120
	v_and_b32_e32 v100, s7, v100
	v_sub_f32_e32 v100, v100, v85
	v_mul_f32_e32 v100, 0x3fb8aa3b, v100
	v_exp_f32_e32 v100, v100
	v_and_b32_e32 v115, s7, v115
	v_sub_f32_e32 v115, v115, v85
	v_mul_f32_e32 v115, 0x3fb8aa3b, v115
	v_exp_f32_e32 v115, v115
	v_and_b32_e32 v92, s7, v92
	v_sub_f32_e32 v92, v92, v85
	v_mul_f32_e32 v92, 0x3fb8aa3b, v92
	v_exp_f32_e32 v92, v92
	s_nop 0
	v_add_f32_e32 v85, v113, v106
	v_add_f32_e32 v85, v85, v116
	v_add_f32_e32 v85, v85, v118
	v_add_f32_e32 v85, v85, v120
	v_add_f32_e32 v85, v85, v100
	v_add_f32_e32 v85, v85, v115
	v_add_f32_e32 v85, v85, v92
	v_mov_b32_e32 v61, v85
	s_nop 1
	v_permlane32_swap_b32_e32 v85, v61
	s_nop 1
	v_add_f32_e32 v85, v85, v61
	s_waitcnt lgkmcnt(0)
	v_bfe_u32 v68, v123, 4, 4
	v_or_b32_e32 v68, v68, v240
	v_and_or_b32 v123, v123, 15, v240
	ds_read_u8 v68, v68
	ds_read_u8 v123, v123 offset:512
	v_bfe_u32 v56, v114, 4, 4
	v_or_b32_e32 v56, v56, v240
	v_and_or_b32 v114, v114, 15, v240
	ds_read_u8 v56, v56
	ds_read_u8 v114, v114 offset:512
	v_bfe_u32 v57, v126, 4, 4
	v_or_b32_e32 v57, v57, v240
	v_and_or_b32 v126, v126, 15, v240
	ds_read_u8 v57, v57
	ds_read_u8 v126, v126 offset:512
	v_bfe_u32 v58, v121, 4, 4
	v_or_b32_e32 v58, v58, v240
	v_and_or_b32 v121, v121, 15, v240
	ds_read_u8 v58, v58
	ds_read_u8 v121, v121 offset:512
	v_bfe_u32 v59, v122, 4, 4
	v_or_b32_e32 v59, v59, v240
	v_and_or_b32 v122, v122, 15, v240
	ds_read_u8 v59, v59
	ds_read_u8 v122, v122 offset:512
	v_bfe_u32 v251, v124, 4, 4
	v_or_b32_e32 v251, v251, v240
	v_and_or_b32 v124, v124, 15, v240
	ds_read_u8 v251, v251
	ds_read_u8 v124, v124 offset:512
	v_bfe_u32 v253, v109, 4, 4
	v_or_b32_e32 v253, v253, v240
	v_and_or_b32 v109, v109, 15, v240
	ds_read_u8 v253, v253
	ds_read_u8 v109, v109 offset:512
	v_bfe_u32 v151, v60, 4, 4
	v_or_b32_e32 v151, v151, v240
	v_and_or_b32 v60, v60, 15, v240
	ds_read_u8 v151, v151
	ds_read_u8 v60, v60 offset:512
	v_div_scale_f32 v134, s[26:27], v85, v85, v113
	v_rcp_f32_e32 v249, v134
	s_nop 0
	v_fma_f32 v136, -v134, v249, 1.0
	v_fmac_f32_e32 v249, v136, v249
	v_div_scale_f32 v136, vcc, v113, v85, v113
	v_mul_f32_e32 v137, v136, v249
	v_fma_f32 v62, -v134, v137, v136
	v_fmac_f32_e32 v137, v62, v249
	v_fma_f32 v136, -v134, v137, v136
	s_nop 0
	v_div_fmas_f32 v136, v136, v249, v137
	v_div_fixup_f32 v62, v136, v85, v113
	v_div_scale_f32 v134, s[26:27], v85, v85, v106
	v_rcp_f32_e32 v249, v134
	s_nop 0
	v_fma_f32 v136, -v134, v249, 1.0
	v_fmac_f32_e32 v249, v136, v249
	v_div_scale_f32 v136, vcc, v106, v85, v106
	v_mul_f32_e32 v137, v136, v249
	v_fma_f32 v64, -v134, v137, v136
	v_fmac_f32_e32 v137, v64, v249
	v_fma_f32 v136, -v134, v137, v136
	s_nop 0
	v_div_fmas_f32 v136, v136, v249, v137
	v_div_fixup_f32 v64, v136, v85, v106
	v_div_scale_f32 v134, s[26:27], v85, v85, v116
	v_rcp_f32_e32 v249, v134
	s_nop 0
	v_fma_f32 v136, -v134, v249, 1.0
	v_fmac_f32_e32 v249, v136, v249
	v_div_scale_f32 v136, vcc, v116, v85, v116
	v_mul_f32_e32 v137, v136, v249
	v_fma_f32 v255, -v134, v137, v136
	v_fmac_f32_e32 v137, v255, v249
	v_fma_f32 v136, -v134, v137, v136
	s_nop 0
	v_div_fmas_f32 v136, v136, v249, v137
	v_div_fixup_f32 v255, v136, v85, v116
	v_div_scale_f32 v134, s[26:27], v85, v85, v118
	v_rcp_f32_e32 v249, v134
	s_nop 0
	v_fma_f32 v136, -v134, v249, 1.0
	v_fmac_f32_e32 v249, v136, v249
	v_div_scale_f32 v136, vcc, v118, v85, v118
	v_mul_f32_e32 v137, v136, v249
	v_fma_f32 v252, -v134, v137, v136
	v_fmac_f32_e32 v137, v252, v249
	v_fma_f32 v136, -v134, v137, v136
	s_nop 0
	v_div_fmas_f32 v136, v136, v249, v137
	v_div_fixup_f32 v252, v136, v85, v118
	v_div_scale_f32 v134, s[26:27], v85, v85, v120
	v_rcp_f32_e32 v249, v134
	s_nop 0
	v_fma_f32 v136, -v134, v249, 1.0
	v_fmac_f32_e32 v249, v136, v249
	v_div_scale_f32 v136, vcc, v120, v85, v120
	v_mul_f32_e32 v137, v136, v249
	v_fma_f32 v129, -v134, v137, v136
	v_fmac_f32_e32 v137, v129, v249
	v_fma_f32 v136, -v134, v137, v136
	s_nop 0
	v_div_fmas_f32 v136, v136, v249, v137
	v_div_fixup_f32 v129, v136, v85, v120
	v_div_scale_f32 v134, s[26:27], v85, v85, v100
	v_rcp_f32_e32 v249, v134
	s_nop 0
	v_fma_f32 v136, -v134, v249, 1.0
	v_fmac_f32_e32 v249, v136, v249
	v_div_scale_f32 v136, vcc, v100, v85, v100
	v_mul_f32_e32 v137, v136, v249
	v_fma_f32 v130, -v134, v137, v136
	v_fmac_f32_e32 v137, v130, v249
	v_fma_f32 v136, -v134, v137, v136
	s_nop 0
	v_div_fmas_f32 v136, v136, v249, v137
	v_div_fixup_f32 v130, v136, v85, v100
	v_div_scale_f32 v134, s[26:27], v85, v85, v115
	v_rcp_f32_e32 v249, v134
	s_nop 0
	v_fma_f32 v136, -v134, v249, 1.0
	v_fmac_f32_e32 v249, v136, v249
	v_div_scale_f32 v136, vcc, v115, v85, v115
	v_mul_f32_e32 v137, v136, v249
	v_fma_f32 v65, -v134, v137, v136
	v_fmac_f32_e32 v137, v65, v249
	v_fma_f32 v136, -v134, v137, v136
	s_nop 0
	v_div_fmas_f32 v136, v136, v249, v137
	v_div_fixup_f32 v65, v136, v85, v115
	v_div_scale_f32 v134, s[26:27], v85, v85, v92
	v_rcp_f32_e32 v249, v134
	s_nop 0
	v_fma_f32 v136, -v134, v249, 1.0
	v_fmac_f32_e32 v249, v136, v249
	v_div_scale_f32 v136, vcc, v92, v85, v92
	v_mul_f32_e32 v137, v136, v249
	v_fma_f32 v133, -v134, v137, v136
	v_fmac_f32_e32 v137, v133, v249
	v_fma_f32 v136, -v134, v137, v136
	s_nop 0
	v_div_fmas_f32 v136, v136, v249, v137
	v_div_fixup_f32 v133, v136, v85, v92
	s_waitcnt lgkmcnt(0)
	v_and_b32_e32 v68, 0x7f, v68
	v_and_b32_e32 v123, 0x7f, v123
	v_lshl_or_b32 v68, v68, 7, v123
	v_xor_b32_e32 v68, 0x3fff, v68
	v_and_b32_e32 v56, 0x7f, v56
	v_and_b32_e32 v114, 0x7f, v114
	v_lshl_or_b32 v56, v56, 7, v114
	v_xor_b32_e32 v56, 0x3fff, v56
	v_and_b32_e32 v57, 0x7f, v57
	v_and_b32_e32 v126, 0x7f, v126
	v_lshl_or_b32 v57, v57, 7, v126
	v_xor_b32_e32 v57, 0x3fff, v57
	v_and_b32_e32 v58, 0x7f, v58
	v_and_b32_e32 v121, 0x7f, v121
	v_lshl_or_b32 v58, v58, 7, v121
	v_xor_b32_e32 v58, 0x3fff, v58
	v_and_b32_e32 v59, 0x7f, v59
	v_and_b32_e32 v122, 0x7f, v122
	v_lshl_or_b32 v59, v59, 7, v122
	v_xor_b32_e32 v59, 0x3fff, v59
	v_and_b32_e32 v251, 0x7f, v251
	v_and_b32_e32 v124, 0x7f, v124
	v_lshl_or_b32 v251, v251, 7, v124
	v_xor_b32_e32 v251, 0x3fff, v251
	v_and_b32_e32 v253, 0x7f, v253
	v_and_b32_e32 v109, 0x7f, v109
	v_lshl_or_b32 v253, v253, 7, v109
	v_xor_b32_e32 v253, 0x3fff, v253
	v_and_b32_e32 v151, 0x7f, v151
	v_and_b32_e32 v60, 0x7f, v60
	v_lshl_or_b32 v151, v151, 7, v60
	v_xor_b32_e32 v151, 0x3fff, v151
	v_mov_b32_e32 v0, v68
	v_mov_b32_e32 v1, v56
	v_mov_b32_e32 v2, v57
	v_mov_b32_e32 v3, v58
	global_store_dwordx4 v241, v[0:3], s[28:29] offset:0
	v_mov_b32_e32 v4, v59
	v_mov_b32_e32 v5, v251
	v_mov_b32_e32 v6, v253
	v_mov_b32_e32 v7, v151
	global_store_dwordx4 v241, v[4:7], s[28:29] offset:16
	v_mov_b32_e32 v8, v62
	v_mov_b32_e32 v9, v64
	v_mov_b32_e32 v10, v255
	v_mov_b32_e32 v11, v252
	global_store_dwordx4 v241, v[8:11], s[30:31] offset:0
	v_mov_b32_e32 v12, v129
	v_mov_b32_e32 v13, v130
	v_mov_b32_e32 v14, v65
	v_mov_b32_e32 v15, v133
	global_store_dwordx4 v241, v[12:15], s[30:31] offset:16
	s_add_i32 s24, s24, 4
	s_add_i32 s22, s22, 1
	s_cmp_lt_u32 s22, 2
	s_cbranch_scc1 .Ltk0_unit

.LBB0_966:
	s_cmp_lt_i32 s56, 15
	s_cselect_b64 s[0:1], -1, 0
	s_and_b64 s[40:41], s[0:1], s[4:5]
	s_andn2_b64 vcc, exec, s[40:41]
	s_cbranch_vccnz .LBB0_1021
	v_mbcnt_lo_u32_b32 v246, -1, 0
	v_mbcnt_hi_u32_b32 v246, -1, v246
	v_readlane_b32 s21, v248, 0
	s_andn2_b32 s26, s21, 63
	v_add_u32_e32 v242, s26, v246
	s_lshr_b32 s21, s21, 6
	s_mov_b32 s4, 0
	s_mov_b32 s5, -1
	s_mov_b32 s6, 0xffffff80
	s_mov_b32 s7, 0xffffffc0
	s_add_u32 s8, s54, 0x1c000000
	s_addc_u32 s9, s55, 0
	s_add_u32 s10, s54, 0x28000000
	s_addc_u32 s11, s55, 0
	s_add_u32 s12, s54, 0x28800000
	s_addc_u32 s13, s55, 0
	s_add_u32 s14, s54, 0x380000
	s_addc_u32 s15, s55, 0
	v_lshrrev_b32_e32 v245, 5, v246
	v_and_b32_e32 v247, 31, v246
	v_lshlrev_b32_e32 v239, 12, v247
	v_lshl_or_b32 v239, v245, 4, v239
	v_lshlrev_b32_e32 v241, 9, v247
	v_lshl_or_b32 v241, v245, 5, v241
	v_lshlrev_b32_e32 v240, 4, v247
	s_lshl_b32 s26, s21, 11
	s_add_i32 s26, s26, 0x10000
	v_add_u32_e32 v240, s26, v240
	v_and_b32_e32 v231, 15, v246
	v_xor_b32_e32 v231, v231, v245
	v_lshlrev_b32_e32 v231, 4, v231
	v_lshl_or_b32 v231, v247, 8, v231
	v_xor_b32_e32 v232, 32, v231
	v_xor_b32_e32 v233, 64, v231
	v_xor_b32_e32 v234, 0x60, v231
	v_xor_b32_e32 v235, 0x80, v231
	v_xor_b32_e32 v236, 0xa0, v231
	v_xor_b32_e32 v237, 0xc0, v231
	v_xor_b32_e32 v238, 0xe0, v231
	v_lshlrev_b32_e32 v247, 2, v245
	v_xor_b32_e32 v160, 0x7f, v247
	v_xor_b32_e32 v161, 0x7e, v247
	v_xor_b32_e32 v162, 0x7d, v247
	v_xor_b32_e32 v163, 0x7c, v247
	v_xor_b32_e32 v164, 0x77, v247
	v_xor_b32_e32 v165, 0x76, v247
	v_xor_b32_e32 v166, 0x75, v247
	v_xor_b32_e32 v167, 0x74, v247
	v_xor_b32_e32 v168, 0x6f, v247
	v_xor_b32_e32 v169, 0x6e, v247
	v_xor_b32_e32 v170, 0x6d, v247
	v_xor_b32_e32 v171, 0x6c, v247
	v_xor_b32_e32 v172, 0x67, v247
	v_xor_b32_e32 v173, 0x66, v247
	v_xor_b32_e32 v174, 0x65, v247
	v_xor_b32_e32 v175, 0x64, v247
	v_xor_b32_e32 v176, 0x5f, v247
	v_xor_b32_e32 v177, 0x5e, v247
	v_xor_b32_e32 v178, 0x5d, v247
	v_xor_b32_e32 v179, 0x5c, v247
	v_xor_b32_e32 v180, 0x57, v247
	v_xor_b32_e32 v181, 0x56, v247
	v_xor_b32_e32 v182, 0x55, v247
	v_xor_b32_e32 v183, 0x54, v247
	v_xor_b32_e32 v184, 0x4f, v247
	v_xor_b32_e32 v185, 0x4e, v247
	v_xor_b32_e32 v186, 0x4d, v247
	v_xor_b32_e32 v187, 0x4c, v247
	v_xor_b32_e32 v188, 0x47, v247
	v_xor_b32_e32 v189, 0x46, v247
	v_xor_b32_e32 v190, 0x45, v247
	v_xor_b32_e32 v191, 0x44, v247
	v_xor_b32_e32 v192, 63, v247
	v_xor_b32_e32 v193, 62, v247
	v_xor_b32_e32 v194, 61, v247
	v_xor_b32_e32 v195, 60, v247
	v_xor_b32_e32 v196, 55, v247
	v_xor_b32_e32 v204, 54, v247
	v_xor_b32_e32 v205, 53, v247
	v_xor_b32_e32 v206, 52, v247
	v_xor_b32_e32 v207, 47, v247
	v_xor_b32_e32 v208, 46, v247
	v_xor_b32_e32 v209, 45, v247
	v_xor_b32_e32 v210, 44, v247
	v_xor_b32_e32 v211, 39, v247
	v_xor_b32_e32 v212, 38, v247
	v_xor_b32_e32 v213, 37, v247
	v_xor_b32_e32 v214, 36, v247
	v_xor_b32_e32 v215, 31, v247
	v_xor_b32_e32 v216, 30, v247
	v_xor_b32_e32 v217, 29, v247
	v_xor_b32_e32 v218, 28, v247
	v_xor_b32_e32 v219, 23, v247
	v_xor_b32_e32 v220, 22, v247
	v_xor_b32_e32 v221, 21, v247
	v_xor_b32_e32 v222, 20, v247
	v_xor_b32_e32 v223, 15, v247
	v_xor_b32_e32 v224, 14, v247
	v_xor_b32_e32 v225, 13, v247
	v_xor_b32_e32 v226, 12, v247
	v_xor_b32_e32 v227, 7, v247
	v_xor_b32_e32 v228, 6, v247
	v_xor_b32_e32 v229, 5, v247
	v_xor_b32_e32 v230, 4, v247
	v_lshrrev_b32_e32 v243, 4, v242
	v_xor_b32_e32 v247, v243, v242
	v_lshlrev_b32_e32 v242, 4, v242
	v_and_b32_e32 v247, 15, v247
	v_lshlrev_b32_e32 v247, 4, v247
	v_lshl_or_b32 v243, v243, 8, v247
	v_mov_b32_e32 v244, 0xff800000
	v_mov_b32_e32 v247, 0x14000
	v_mov_b32_e32 v128, 0x20021001
	ds_write_b32 v247, v128 offset:0
	v_mov_b32_e32 v128, 0x40043003
	ds_write_b32 v247, v128 offset:4
	v_mov_b32_e32 v128, 0x60065005
	ds_write_b32 v247, v128 offset:8
	v_mov_b32_e32 v128, 0x80087007
	ds_write_b32 v247, v128 offset:12
	v_mov_b32_e32 v128, 0xa00a9009
	ds_write_b32 v247, v128 offset:16
	v_mov_b32_e32 v128, 0xc00cb00b
	ds_write_b32 v247, v128 offset:20
	v_mov_b32_e32 v128, 0xe00ed00d
	ds_write_b32 v247, v128 offset:24
	v_mov_b32_e32 v128, 0x2112f00f
	ds_write_b32 v247, v128 offset:28
	v_mov_b32_e32 v128, 0x41143113
	ds_write_b32 v247, v128 offset:32
	v_mov_b32_e32 v128, 0x61165115
	ds_write_b32 v247, v128 offset:36
	v_mov_b32_e32 v128, 0x32237117
	ds_write_b32 v247, v128 offset:40
	v_mov_b32_e32 v128, 0x4224
	ds_write_b32 v247, v128 offset:44
	v_mov_b32_e32 v128, 0x22221111
	ds_write_b32 v247, v128 offset:48
	v_mov_b32_e32 v128, 0x3333
	ds_write_b32 v247, v128 offset:52
	v_mov_b32_e32 v128, 0
	ds_write_b32 v247, v128 offset:56
	v_mov_b32_e32 v128, 0
	ds_write_b32 v247, v128 offset:60
	v_mov_b32_e32 v246, 0x14000
	s_and_b32 s25, s2, 7
	s_lshl_b32 s25, s25, 3
	s_bfe_u32 s26, s2, 0x30003
	s_add_i32 s25, s25, s26
	s_lshl_b32 s23, s25, 8
	s_lshl_b32 s26, s21, 5
	s_add_i32 s23, s23, s26
	s_lshr_b32 s24, s2, 6
	s_mov_b32 s22, 0
